# early closing barrier with 2 tail MFMAs at s_setprio 3 (fits the ~40-cycle slack of the load segment)
# baseline (speedup 1.0000x reference)
.LBB0_200:
	ds_read_b128 v[148:151], v169
	ds_read_b128 v[152:155], v169 offset:1024
	ds_read_b128 v[156:159], v169 offset:2048
	ds_read_b128 v[160:163], v169 offset:3072
	ds_read_b128 v[174:177], v170
	ds_read_b128 v[178:181], v170 offset:1024
	ds_read_b128 v[182:185], v170 offset:2048
	ds_read_b128 v[186:189], v170 offset:3072
	s_add_u32 s26, s6, 0xfff00800
	s_addc_u32 s27, s7, -1
	s_cmp_eq_u32 s34, 60
	s_cselect_b32 s29, s17, s27
	s_cselect_b32 s28, s23, s26
	s_cselect_b32 s27, s15, s31
	s_cselect_b32 s26, s25, s30
	v_lshl_add_u64 v[190:191], s[6:7], 0, v[138:139]
	s_add_i32 m0, s41, 0xc000
	s_nop 0
	global_load_lds_dwordx4 v[190:191], off
	v_lshl_add_u64 v[190:191], s[6:7], 0, v[140:141]
	s_add_i32 m0, s41, 0xe000
	s_nop 0
	global_load_lds_dwordx4 v[190:191], off
	ds_read_b128 v[190:193], v171
	ds_read_b128 v[194:197], v171 offset:1024
	ds_read_b128 v[198:201], v171 offset:2048
	ds_read_b128 v[202:205], v171 offset:3072
	ds_read_b128 v[206:209], v171 offset:4096
	ds_read_b128 v[210:213], v171 offset:5120
	ds_read_b128 v[214:217], v171 offset:6144
	ds_read_b128 v[218:221], v171 offset:7168
	s_waitcnt vmcnt(8)
	s_waitcnt lgkmcnt(0)
	s_barrier
	v_mfma_f32_16x16x32_bf16 v[124:127], v[148:151], v[190:193], v[124:127]
	v_mfma_f32_16x16x32_bf16 v[124:127], v[152:155], v[194:197], v[124:127]
	v_mfma_f32_16x16x32_bf16 v[120:123], v[160:163], v[194:197], v[120:123]
	v_mfma_f32_16x16x32_bf16 v[120:123], v[156:159], v[190:193], v[120:123]
	v_mfma_f32_16x16x32_bf16 v[60:63], v[174:177], v[190:193], v[60:63]
	v_mfma_f32_16x16x32_bf16 v[60:63], v[178:181], v[194:197], v[60:63]
	v_mfma_f32_16x16x32_bf16 v[56:59], v[186:189], v[194:197], v[56:59]
	v_mfma_f32_16x16x32_bf16 v[56:59], v[182:185], v[190:193], v[56:59]
	v_mfma_f32_16x16x32_bf16 v[48:51], v[182:185], v[198:201], v[48:51]
	v_mfma_f32_16x16x32_bf16 v[48:51], v[186:189], v[202:205], v[48:51]
	v_mfma_f32_16x16x32_bf16 v[52:55], v[178:181], v[202:205], v[52:55]
	v_mfma_f32_16x16x32_bf16 v[52:55], v[174:177], v[198:201], v[52:55]
	v_mfma_f32_16x16x32_bf16 v[112:115], v[156:159], v[198:201], v[112:115]
	v_mfma_f32_16x16x32_bf16 v[112:115], v[160:163], v[202:205], v[112:115]
	v_mfma_f32_16x16x32_bf16 v[116:119], v[152:155], v[202:205], v[116:119]
	v_mfma_f32_16x16x32_bf16 v[116:119], v[148:151], v[198:201], v[116:119]
	v_mfma_f32_16x16x32_bf16 v[108:111], v[148:151], v[206:209], v[108:111]
	v_mfma_f32_16x16x32_bf16 v[108:111], v[152:155], v[210:213], v[108:111]
	v_mfma_f32_16x16x32_bf16 v[104:107], v[160:163], v[210:213], v[104:107]
	v_mfma_f32_16x16x32_bf16 v[104:107], v[156:159], v[206:209], v[104:107]
	v_mfma_f32_16x16x32_bf16 v[44:47], v[174:177], v[206:209], v[44:47]
	v_mfma_f32_16x16x32_bf16 v[44:47], v[178:181], v[210:213], v[44:47]
	v_mfma_f32_16x16x32_bf16 v[40:43], v[186:189], v[210:213], v[40:43]
	v_mfma_f32_16x16x32_bf16 v[40:43], v[182:185], v[206:209], v[40:43]
	v_mfma_f32_16x16x32_bf16 v[32:35], v[182:185], v[214:217], v[32:35]
	v_mfma_f32_16x16x32_bf16 v[32:35], v[186:189], v[218:221], v[32:35]
	v_mfma_f32_16x16x32_bf16 v[36:39], v[178:181], v[218:221], v[36:39]
	v_mfma_f32_16x16x32_bf16 v[36:39], v[174:177], v[214:217], v[36:39]
	v_mfma_f32_16x16x32_bf16 v[96:99], v[156:159], v[214:217], v[96:99]
	v_mfma_f32_16x16x32_bf16 v[96:99], v[160:163], v[218:221], v[96:99]
	s_barrier
	s_setprio 3
	v_mfma_f32_16x16x32_bf16 v[100:103], v[152:155], v[218:221], v[100:103]
	v_mfma_f32_16x16x32_bf16 v[100:103], v[148:151], v[214:217], v[100:103]
	s_setprio 0
	s_add_i32 s35, s55, s36
	v_lshl_add_u64 v[222:223], s[26:27], 0, v[130:131]
	s_mov_b32 m0, s35
	v_lshl_add_u64 v[224:225], s[26:27], 0, v[134:135]
	global_load_lds_dwordx4 v[222:223], off
	s_add_i32 m0, s35, 0x2000
	s_add_u32 s58, s26, 0x100000
	s_addc_u32 s59, s27, 0
	s_add_i32 s35, s56, s36
	global_load_lds_dwordx4 v[224:225], off
	v_lshl_add_u64 v[190:191], s[58:59], 0, v[130:131]
	s_mov_b32 m0, s35
	v_lshl_add_u64 v[226:227], s[28:29], 0, v[128:129]
	global_load_lds_dwordx4 v[190:191], off
	v_lshl_add_u64 v[190:191], s[58:59], 0, v[134:135]
	s_add_i32 m0, s35, 0x2000
	v_lshl_add_u64 v[228:229], s[28:29], 0, v[132:133]
	global_load_lds_dwordx4 v[190:191], off
	s_mov_b32 m0, s41
	s_nop 0
	global_load_lds_dwordx4 v[226:227], off
	s_mov_b32 m0, s42
	s_nop 0
	global_load_lds_dwordx4 v[228:229], off
	ds_read_b128 v[190:193], v171 offset:16384
	ds_read_b128 v[194:197], v171 offset:17408
	ds_read_b128 v[198:201], v171 offset:18432
	ds_read_b128 v[202:205], v171 offset:19456
	ds_read_b128 v[206:209], v171 offset:20480
	ds_read_b128 v[210:213], v171 offset:21504
	ds_read_b128 v[214:217], v171 offset:22528
	ds_read_b128 v[218:221], v171 offset:23552
	s_waitcnt vmcnt(8)
	s_waitcnt lgkmcnt(0)
	s_barrier
	v_mfma_f32_16x16x32_bf16 v[92:95], v[148:151], v[190:193], v[92:95]
	v_mfma_f32_16x16x32_bf16 v[92:95], v[152:155], v[194:197], v[92:95]
	v_mfma_f32_16x16x32_bf16 v[88:91], v[160:163], v[194:197], v[88:91]
	v_mfma_f32_16x16x32_bf16 v[88:91], v[156:159], v[190:193], v[88:91]
	v_mfma_f32_16x16x32_bf16 v[28:31], v[174:177], v[190:193], v[28:31]
	v_mfma_f32_16x16x32_bf16 v[28:31], v[178:181], v[194:197], v[28:31]
	v_mfma_f32_16x16x32_bf16 v[24:27], v[186:189], v[194:197], v[24:27]
	v_mfma_f32_16x16x32_bf16 v[24:27], v[182:185], v[190:193], v[24:27]
	v_mfma_f32_16x16x32_bf16 v[16:19], v[182:185], v[198:201], v[16:19]
	v_mfma_f32_16x16x32_bf16 v[16:19], v[186:189], v[202:205], v[16:19]
	v_mfma_f32_16x16x32_bf16 v[20:23], v[178:181], v[202:205], v[20:23]
	v_mfma_f32_16x16x32_bf16 v[20:23], v[174:177], v[198:201], v[20:23]
	v_mfma_f32_16x16x32_bf16 v[80:83], v[156:159], v[198:201], v[80:83]
	v_mfma_f32_16x16x32_bf16 v[80:83], v[160:163], v[202:205], v[80:83]
	v_mfma_f32_16x16x32_bf16 v[84:87], v[152:155], v[202:205], v[84:87]
	v_mfma_f32_16x16x32_bf16 v[84:87], v[148:151], v[198:201], v[84:87]
	v_mfma_f32_16x16x32_bf16 v[76:79], v[148:151], v[206:209], v[76:79]
	v_mfma_f32_16x16x32_bf16 v[76:79], v[152:155], v[210:213], v[76:79]
	v_mfma_f32_16x16x32_bf16 v[72:75], v[160:163], v[210:213], v[72:75]
	v_mfma_f32_16x16x32_bf16 v[72:75], v[156:159], v[206:209], v[72:75]
	v_mfma_f32_16x16x32_bf16 v[12:15], v[174:177], v[206:209], v[12:15]
	v_mfma_f32_16x16x32_bf16 v[12:15], v[178:181], v[210:213], v[12:15]
	v_mfma_f32_16x16x32_bf16 v[8:11], v[186:189], v[210:213], v[8:11]
	v_mfma_f32_16x16x32_bf16 v[8:11], v[182:185], v[206:209], v[8:11]
	v_mfma_f32_16x16x32_bf16 v[0:3], v[182:185], v[214:217], v[0:3]
	v_mfma_f32_16x16x32_bf16 v[0:3], v[186:189], v[218:221], v[0:3]
	v_mfma_f32_16x16x32_bf16 v[4:7], v[178:181], v[218:221], v[4:7]
	v_mfma_f32_16x16x32_bf16 v[4:7], v[174:177], v[214:217], v[4:7]
	v_mfma_f32_16x16x32_bf16 v[64:67], v[156:159], v[214:217], v[64:67]
	v_mfma_f32_16x16x32_bf16 v[64:67], v[160:163], v[218:221], v[64:67]
	s_barrier
	s_setprio 3
	v_mfma_f32_16x16x32_bf16 v[68:71], v[152:155], v[218:221], v[68:71]
	v_mfma_f32_16x16x32_bf16 v[68:71], v[148:151], v[214:217], v[68:71]
	s_setprio 0
	s_add_i32 s35, 0, 0x18000
	v_add_u32_e32 v136, s35, v165
	s_add_i32 s57, 0, 0x1c000
	ds_read_b128 v[148:151], v136
	ds_read_b128 v[152:155], v136 offset:1024
	ds_read_b128 v[156:159], v136 offset:2048
	ds_read_b128 v[160:163], v136 offset:3072
	v_add_u32_e32 v136, s57, v165
	ds_read_b128 v[174:177], v136
	ds_read_b128 v[178:181], v136 offset:1024
	ds_read_b128 v[182:185], v136 offset:2048
	ds_read_b128 v[186:189], v136 offset:3072
	s_add_u32 s28, s28, 0x100000
	s_addc_u32 s29, s29, 0
	s_mov_b32 m0, s43
	v_lshl_add_u64 v[190:191], s[28:29], 0, v[128:129]
	global_load_lds_dwordx4 v[190:191], off
	v_lshl_add_u64 v[190:191], s[28:29], 0, v[132:133]
	s_mov_b32 m0, s44
	s_nop 0
	global_load_lds_dwordx4 v[190:191], off
	ds_read_b128 v[190:193], v171 offset:32768
	ds_read_b128 v[194:197], v171 offset:33792
	ds_read_b128 v[198:201], v171 offset:34816
	ds_read_b128 v[202:205], v171 offset:35840
	ds_read_b128 v[206:209], v171 offset:36864
	ds_read_b128 v[210:213], v171 offset:37888
	ds_read_b128 v[214:217], v171 offset:38912
	ds_read_b128 v[218:221], v171 offset:39936
	s_waitcnt vmcnt(8)
	s_waitcnt lgkmcnt(0)
	s_barrier
	v_mfma_f32_16x16x32_bf16 v[124:127], v[148:151], v[190:193], v[124:127]
	v_mfma_f32_16x16x32_bf16 v[124:127], v[152:155], v[194:197], v[124:127]
	v_mfma_f32_16x16x32_bf16 v[120:123], v[160:163], v[194:197], v[120:123]
	v_mfma_f32_16x16x32_bf16 v[120:123], v[156:159], v[190:193], v[120:123]
	v_mfma_f32_16x16x32_bf16 v[60:63], v[174:177], v[190:193], v[60:63]
	v_mfma_f32_16x16x32_bf16 v[60:63], v[178:181], v[194:197], v[60:63]
	v_mfma_f32_16x16x32_bf16 v[56:59], v[186:189], v[194:197], v[56:59]
	v_mfma_f32_16x16x32_bf16 v[56:59], v[182:185], v[190:193], v[56:59]
	v_mfma_f32_16x16x32_bf16 v[48:51], v[182:185], v[198:201], v[48:51]
	v_mfma_f32_16x16x32_bf16 v[48:51], v[186:189], v[202:205], v[48:51]
	v_mfma_f32_16x16x32_bf16 v[52:55], v[178:181], v[202:205], v[52:55]
	v_mfma_f32_16x16x32_bf16 v[52:55], v[174:177], v[198:201], v[52:55]
	v_mfma_f32_16x16x32_bf16 v[112:115], v[156:159], v[198:201], v[112:115]
	v_mfma_f32_16x16x32_bf16 v[112:115], v[160:163], v[202:205], v[112:115]
	v_mfma_f32_16x16x32_bf16 v[116:119], v[152:155], v[202:205], v[116:119]
	v_mfma_f32_16x16x32_bf16 v[116:119], v[148:151], v[198:201], v[116:119]
	v_mfma_f32_16x16x32_bf16 v[108:111], v[148:151], v[206:209], v[108:111]
	v_mfma_f32_16x16x32_bf16 v[108:111], v[152:155], v[210:213], v[108:111]
	v_mfma_f32_16x16x32_bf16 v[104:107], v[160:163], v[210:213], v[104:107]
	v_mfma_f32_16x16x32_bf16 v[104:107], v[156:159], v[206:209], v[104:107]
	v_mfma_f32_16x16x32_bf16 v[44:47], v[174:177], v[206:209], v[44:47]
	v_mfma_f32_16x16x32_bf16 v[44:47], v[178:181], v[210:213], v[44:47]
	v_mfma_f32_16x16x32_bf16 v[40:43], v[186:189], v[210:213], v[40:43]
	v_mfma_f32_16x16x32_bf16 v[40:43], v[182:185], v[206:209], v[40:43]
	v_mfma_f32_16x16x32_bf16 v[32:35], v[182:185], v[214:217], v[32:35]
	v_mfma_f32_16x16x32_bf16 v[32:35], v[186:189], v[218:221], v[32:35]
	v_mfma_f32_16x16x32_bf16 v[36:39], v[178:181], v[218:221], v[36:39]
	v_mfma_f32_16x16x32_bf16 v[36:39], v[174:177], v[214:217], v[36:39]
	v_mfma_f32_16x16x32_bf16 v[96:99], v[156:159], v[214:217], v[96:99]
	v_mfma_f32_16x16x32_bf16 v[96:99], v[160:163], v[218:221], v[96:99]
	s_barrier
	s_setprio 3
	v_mfma_f32_16x16x32_bf16 v[100:103], v[152:155], v[218:221], v[100:103]
	v_mfma_f32_16x16x32_bf16 v[100:103], v[148:151], v[214:217], v[100:103]
	s_setprio 0
	s_add_i32 s28, s35, s36
	v_lshl_add_u64 v[190:191], v[222:223], 0, s[12:13]
	s_mov_b32 m0, s28
	s_nop 0
	global_load_lds_dwordx4 v[190:191], off
	s_add_i32 m0, s28, 0x2000
	s_add_u32 s26, s26, 0x100800
	v_lshl_add_u64 v[190:191], v[224:225], 0, s[12:13]
	s_addc_u32 s27, s27, 0
	s_add_i32 s28, s57, s36
	global_load_lds_dwordx4 v[190:191], off
	v_lshl_add_u64 v[190:191], s[26:27], 0, v[130:131]
	s_mov_b32 m0, s28
	s_nop 0
	global_load_lds_dwordx4 v[190:191], off
	v_lshl_add_u64 v[190:191], s[26:27], 0, v[134:135]
	s_add_i32 m0, s28, 0x2000
	s_nop 0
	global_load_lds_dwordx4 v[190:191], off
	v_lshl_add_u64 v[190:191], v[226:227], 0, s[12:13]
	s_mov_b32 m0, s49
	s_nop 0
	global_load_lds_dwordx4 v[190:191], off
	v_lshl_add_u64 v[190:191], v[228:229], 0, s[12:13]
	s_mov_b32 m0, s50
	s_nop 0
	global_load_lds_dwordx4 v[190:191], off
	ds_read_b128 v[190:193], v171 offset:49152
	ds_read_b128 v[194:197], v171 offset:50176
	ds_read_b128 v[198:201], v171 offset:51200
	ds_read_b128 v[202:205], v171 offset:52224
	ds_read_b128 v[206:209], v171 offset:53248
	ds_read_b128 v[210:213], v171 offset:54272
	ds_read_b128 v[214:217], v171 offset:55296
	ds_read_b128 v[218:221], v171 offset:56320
	s_waitcnt vmcnt(8)
	s_waitcnt lgkmcnt(0)
	s_barrier
	v_mfma_f32_16x16x32_bf16 v[92:95], v[148:151], v[190:193], v[92:95]
	v_mfma_f32_16x16x32_bf16 v[92:95], v[152:155], v[194:197], v[92:95]
	v_mfma_f32_16x16x32_bf16 v[88:91], v[160:163], v[194:197], v[88:91]
	v_mfma_f32_16x16x32_bf16 v[88:91], v[156:159], v[190:193], v[88:91]
	v_mfma_f32_16x16x32_bf16 v[28:31], v[174:177], v[190:193], v[28:31]
	v_mfma_f32_16x16x32_bf16 v[28:31], v[178:181], v[194:197], v[28:31]
	v_mfma_f32_16x16x32_bf16 v[24:27], v[186:189], v[194:197], v[24:27]
	v_mfma_f32_16x16x32_bf16 v[24:27], v[182:185], v[190:193], v[24:27]
	v_mfma_f32_16x16x32_bf16 v[16:19], v[182:185], v[198:201], v[16:19]
	v_mfma_f32_16x16x32_bf16 v[16:19], v[186:189], v[202:205], v[16:19]
	v_mfma_f32_16x16x32_bf16 v[20:23], v[178:181], v[202:205], v[20:23]
	v_mfma_f32_16x16x32_bf16 v[20:23], v[174:177], v[198:201], v[20:23]
	v_mfma_f32_16x16x32_bf16 v[80:83], v[156:159], v[198:201], v[80:83]
	v_mfma_f32_16x16x32_bf16 v[80:83], v[160:163], v[202:205], v[80:83]
	v_mfma_f32_16x16x32_bf16 v[84:87], v[152:155], v[202:205], v[84:87]
	v_mfma_f32_16x16x32_bf16 v[84:87], v[148:151], v[198:201], v[84:87]
	v_mfma_f32_16x16x32_bf16 v[76:79], v[148:151], v[206:209], v[76:79]
	v_mfma_f32_16x16x32_bf16 v[76:79], v[152:155], v[210:213], v[76:79]
	v_mfma_f32_16x16x32_bf16 v[72:75], v[160:163], v[210:213], v[72:75]
	v_mfma_f32_16x16x32_bf16 v[72:75], v[156:159], v[206:209], v[72:75]
	v_mfma_f32_16x16x32_bf16 v[12:15], v[174:177], v[206:209], v[12:15]
	v_mfma_f32_16x16x32_bf16 v[12:15], v[178:181], v[210:213], v[12:15]
	v_mfma_f32_16x16x32_bf16 v[8:11], v[186:189], v[210:213], v[8:11]
	v_mfma_f32_16x16x32_bf16 v[8:11], v[182:185], v[206:209], v[8:11]
	v_mfma_f32_16x16x32_bf16 v[0:3], v[182:185], v[214:217], v[0:3]
	v_mfma_f32_16x16x32_bf16 v[0:3], v[186:189], v[218:221], v[0:3]
	v_mfma_f32_16x16x32_bf16 v[4:7], v[178:181], v[218:221], v[4:7]
	v_mfma_f32_16x16x32_bf16 v[4:7], v[174:177], v[214:217], v[4:7]
	v_mfma_f32_16x16x32_bf16 v[64:67], v[156:159], v[214:217], v[64:67]
	v_mfma_f32_16x16x32_bf16 v[64:67], v[160:163], v[218:221], v[64:67]
	s_barrier
	s_setprio 3
	v_mfma_f32_16x16x32_bf16 v[68:71], v[152:155], v[218:221], v[68:71]
	v_mfma_f32_16x16x32_bf16 v[68:71], v[148:151], v[214:217], v[68:71]
	s_setprio 0
	s_add_i32 s34, s34, 2
	s_add_u32 s6, s6, 0x1000
	s_addc_u32 s7, s7, 0
	s_add_u32 s30, s30, 0x1000
	s_addc_u32 s31, s31, 0
	s_cmp_gt_u32 s34, 61
	s_cbranch_scc0 .LBB0_200

.LBB0_333:
	ds_read_b128 v[144:147], v152
	ds_read_b128 v[156:159], v152 offset:1024
	ds_read_b128 v[160:163], v152 offset:2048
	ds_read_b128 v[164:167], v152 offset:3072
	ds_read_b128 v[168:171], v153
	ds_read_b128 v[172:175], v153 offset:1024
	ds_read_b128 v[176:179], v153 offset:2048
	ds_read_b128 v[180:183], v153 offset:3072
	s_add_u32 s28, s24, 0x100
	s_addc_u32 s29, s25, 0
	s_cmp_eq_u32 s56, 60
	s_cselect_b32 s35, s13, s29
	s_cselect_b32 s34, s52, s28
	s_cselect_b32 s31, s11, s55
	s_cselect_b32 s30, s53, s54
	v_lshl_add_u64 v[184:185], s[24:25], 0, v[136:137]
	s_add_i32 m0, s21, 0xc000
	s_nop 0
	global_load_lds_dwordx4 v[184:185], off
	v_lshl_add_u64 v[184:185], s[24:25], 0, v[138:139]
	s_add_i32 m0, s21, 0xe000
	s_nop 0
	global_load_lds_dwordx4 v[184:185], off
	ds_read_b128 v[184:187], v154
	ds_read_b128 v[188:191], v154 offset:1024
	ds_read_b128 v[192:195], v154 offset:2048
	ds_read_b128 v[196:199], v154 offset:3072
	ds_read_b128 v[200:203], v154 offset:4096
	ds_read_b128 v[204:207], v154 offset:5120
	ds_read_b128 v[208:211], v154 offset:6144
	ds_read_b128 v[212:215], v154 offset:7168
	s_waitcnt vmcnt(8)
	s_waitcnt lgkmcnt(0)
	s_barrier
	v_mfma_f32_16x16x32_bf16 v[124:127], v[144:147], v[184:187], v[124:127]
	v_mfma_f32_16x16x32_bf16 v[124:127], v[156:159], v[188:191], v[124:127]
	v_mfma_f32_16x16x32_bf16 v[120:123], v[164:167], v[188:191], v[120:123]
	v_mfma_f32_16x16x32_bf16 v[120:123], v[160:163], v[184:187], v[120:123]
	v_mfma_f32_16x16x32_bf16 v[112:115], v[168:171], v[184:187], v[112:115]
	v_mfma_f32_16x16x32_bf16 v[112:115], v[172:175], v[188:191], v[112:115]
	v_mfma_f32_16x16x32_bf16 v[104:107], v[180:183], v[188:191], v[104:107]
	v_mfma_f32_16x16x32_bf16 v[104:107], v[176:179], v[184:187], v[104:107]
	v_mfma_f32_16x16x32_bf16 v[88:91], v[176:179], v[192:195], v[88:91]
	v_mfma_f32_16x16x32_bf16 v[88:91], v[180:183], v[196:199], v[88:91]
	v_mfma_f32_16x16x32_bf16 v[96:99], v[172:175], v[196:199], v[96:99]
	v_mfma_f32_16x16x32_bf16 v[96:99], v[168:171], v[192:195], v[96:99]
	v_mfma_f32_16x16x32_bf16 v[108:111], v[160:163], v[192:195], v[108:111]
	v_mfma_f32_16x16x32_bf16 v[108:111], v[164:167], v[196:199], v[108:111]
	v_mfma_f32_16x16x32_bf16 v[116:119], v[156:159], v[196:199], v[116:119]
	v_mfma_f32_16x16x32_bf16 v[116:119], v[144:147], v[192:195], v[116:119]
	v_mfma_f32_16x16x32_bf16 v[100:103], v[144:147], v[200:203], v[100:103]
	v_mfma_f32_16x16x32_bf16 v[100:103], v[156:159], v[204:207], v[100:103]
	v_mfma_f32_16x16x32_bf16 v[92:95], v[164:167], v[204:207], v[92:95]
	v_mfma_f32_16x16x32_bf16 v[92:95], v[160:163], v[200:203], v[92:95]
	v_mfma_f32_16x16x32_bf16 v[80:83], v[168:171], v[200:203], v[80:83]
	v_mfma_f32_16x16x32_bf16 v[80:83], v[172:175], v[204:207], v[80:83]
	v_mfma_f32_16x16x32_bf16 v[72:75], v[180:183], v[204:207], v[72:75]
	v_mfma_f32_16x16x32_bf16 v[72:75], v[176:179], v[200:203], v[72:75]
	v_mfma_f32_16x16x32_bf16 v[64:67], v[176:179], v[208:211], v[64:67]
	v_mfma_f32_16x16x32_bf16 v[64:67], v[180:183], v[212:215], v[64:67]
	v_mfma_f32_16x16x32_bf16 v[68:71], v[172:175], v[212:215], v[68:71]
	v_mfma_f32_16x16x32_bf16 v[68:71], v[168:171], v[208:211], v[68:71]
	v_mfma_f32_16x16x32_bf16 v[76:79], v[160:163], v[208:211], v[76:79]
	v_mfma_f32_16x16x32_bf16 v[76:79], v[164:167], v[212:215], v[76:79]
	s_barrier
	s_setprio 3
	v_mfma_f32_16x16x32_bf16 v[84:87], v[156:159], v[212:215], v[84:87]
	v_mfma_f32_16x16x32_bf16 v[84:87], v[144:147], v[208:211], v[84:87]
	s_setprio 0
	s_add_i32 s24, s49, s41
	v_lshl_add_u64 v[216:217], s[30:31], 0, v[130:131]
	s_mov_b32 m0, s24
	v_lshl_add_u64 v[218:219], s[30:31], 0, v[134:135]
	global_load_lds_dwordx4 v[216:217], off
	s_add_i32 m0, s24, 0x2000
	s_add_u32 s24, s30, 0x100000
	s_addc_u32 s25, s31, 0
	s_add_i32 s57, s50, s41
	global_load_lds_dwordx4 v[218:219], off
	v_lshl_add_u64 v[184:185], s[24:25], 0, v[130:131]
	s_mov_b32 m0, s57
	v_lshl_add_u64 v[220:221], s[34:35], 0, v[128:129]
	global_load_lds_dwordx4 v[184:185], off
	v_lshl_add_u64 v[184:185], s[24:25], 0, v[134:135]
	s_add_i32 m0, s57, 0x2000
	v_lshl_add_u64 v[222:223], s[34:35], 0, v[132:133]
	global_load_lds_dwordx4 v[184:185], off
	s_mov_b32 m0, s21
	s_nop 0
	global_load_lds_dwordx4 v[220:221], off
	s_mov_b32 m0, s42
	s_nop 0
	global_load_lds_dwordx4 v[222:223], off
	ds_read_b128 v[184:187], v154 offset:16384
	ds_read_b128 v[188:191], v154 offset:17408
	ds_read_b128 v[192:195], v154 offset:18432
	ds_read_b128 v[196:199], v154 offset:19456
	ds_read_b128 v[200:203], v154 offset:20480
	ds_read_b128 v[204:207], v154 offset:21504
	ds_read_b128 v[208:211], v154 offset:22528
	ds_read_b128 v[212:215], v154 offset:23552
	s_waitcnt vmcnt(8)
	s_waitcnt lgkmcnt(0)
	s_barrier
	v_mfma_f32_16x16x32_bf16 v[60:63], v[144:147], v[184:187], v[60:63]
	v_mfma_f32_16x16x32_bf16 v[60:63], v[156:159], v[188:191], v[60:63]
	v_mfma_f32_16x16x32_bf16 v[56:59], v[164:167], v[188:191], v[56:59]
	v_mfma_f32_16x16x32_bf16 v[56:59], v[160:163], v[184:187], v[56:59]
	v_mfma_f32_16x16x32_bf16 v[48:51], v[168:171], v[184:187], v[48:51]
	v_mfma_f32_16x16x32_bf16 v[48:51], v[172:175], v[188:191], v[48:51]
	v_mfma_f32_16x16x32_bf16 v[40:43], v[180:183], v[188:191], v[40:43]
	v_mfma_f32_16x16x32_bf16 v[40:43], v[176:179], v[184:187], v[40:43]
	v_mfma_f32_16x16x32_bf16 v[24:27], v[176:179], v[192:195], v[24:27]
	v_mfma_f32_16x16x32_bf16 v[24:27], v[180:183], v[196:199], v[24:27]
	v_mfma_f32_16x16x32_bf16 v[32:35], v[172:175], v[196:199], v[32:35]
	v_mfma_f32_16x16x32_bf16 v[32:35], v[168:171], v[192:195], v[32:35]
	v_mfma_f32_16x16x32_bf16 v[44:47], v[160:163], v[192:195], v[44:47]
	v_mfma_f32_16x16x32_bf16 v[44:47], v[164:167], v[196:199], v[44:47]
	v_mfma_f32_16x16x32_bf16 v[52:55], v[156:159], v[196:199], v[52:55]
	v_mfma_f32_16x16x32_bf16 v[52:55], v[144:147], v[192:195], v[52:55]
	v_mfma_f32_16x16x32_bf16 v[36:39], v[144:147], v[200:203], v[36:39]
	v_mfma_f32_16x16x32_bf16 v[36:39], v[156:159], v[204:207], v[36:39]
	v_mfma_f32_16x16x32_bf16 v[28:31], v[164:167], v[204:207], v[28:31]
	v_mfma_f32_16x16x32_bf16 v[28:31], v[160:163], v[200:203], v[28:31]
	v_mfma_f32_16x16x32_bf16 v[16:19], v[168:171], v[200:203], v[16:19]
	v_mfma_f32_16x16x32_bf16 v[16:19], v[172:175], v[204:207], v[16:19]
	v_mfma_f32_16x16x32_bf16 v[8:11], v[180:183], v[204:207], v[8:11]
	v_mfma_f32_16x16x32_bf16 v[8:11], v[176:179], v[200:203], v[8:11]
	v_mfma_f32_16x16x32_bf16 v[0:3], v[176:179], v[208:211], v[0:3]
	v_mfma_f32_16x16x32_bf16 v[0:3], v[180:183], v[212:215], v[0:3]
	v_mfma_f32_16x16x32_bf16 v[4:7], v[172:175], v[212:215], v[4:7]
	v_mfma_f32_16x16x32_bf16 v[4:7], v[168:171], v[208:211], v[4:7]
	v_mfma_f32_16x16x32_bf16 v[12:15], v[160:163], v[208:211], v[12:15]
	v_mfma_f32_16x16x32_bf16 v[12:15], v[164:167], v[212:215], v[12:15]
	s_barrier
	s_setprio 3
	v_mfma_f32_16x16x32_bf16 v[20:23], v[156:159], v[212:215], v[20:23]
	v_mfma_f32_16x16x32_bf16 v[20:23], v[144:147], v[208:211], v[20:23]
	s_setprio 0
	s_add_i32 s57, 0, 0x18000
	v_add_u32_e32 v155, s57, v149
	s_add_i32 s58, 0, 0x1c000
	ds_read_b128 v[144:147], v155
	ds_read_b128 v[156:159], v155 offset:1024
	ds_read_b128 v[160:163], v155 offset:2048
	ds_read_b128 v[164:167], v155 offset:3072
	v_add_u32_e32 v155, s58, v149
	ds_read_b128 v[168:171], v155
	ds_read_b128 v[172:175], v155 offset:1024
	ds_read_b128 v[176:179], v155 offset:2048
	ds_read_b128 v[180:183], v155 offset:3072
	s_add_u32 s24, s34, 0x100000
	s_addc_u32 s25, s35, 0
	s_mov_b32 m0, s43
	v_lshl_add_u64 v[184:185], s[24:25], 0, v[128:129]
	global_load_lds_dwordx4 v[184:185], off
	v_lshl_add_u64 v[184:185], s[24:25], 0, v[132:133]
	s_mov_b32 m0, s44
	s_nop 0
	global_load_lds_dwordx4 v[184:185], off
	ds_read_b128 v[184:187], v154 offset:32768
	ds_read_b128 v[188:191], v154 offset:33792
	ds_read_b128 v[192:195], v154 offset:34816
	ds_read_b128 v[196:199], v154 offset:35840
	ds_read_b128 v[200:203], v154 offset:36864
	ds_read_b128 v[204:207], v154 offset:37888
	ds_read_b128 v[208:211], v154 offset:38912
	ds_read_b128 v[212:215], v154 offset:39936
	s_waitcnt vmcnt(8)
	s_waitcnt lgkmcnt(0)
	s_barrier
	v_mfma_f32_16x16x32_bf16 v[124:127], v[144:147], v[184:187], v[124:127]
	v_mfma_f32_16x16x32_bf16 v[124:127], v[156:159], v[188:191], v[124:127]
	v_mfma_f32_16x16x32_bf16 v[120:123], v[164:167], v[188:191], v[120:123]
	v_mfma_f32_16x16x32_bf16 v[120:123], v[160:163], v[184:187], v[120:123]
	v_mfma_f32_16x16x32_bf16 v[112:115], v[168:171], v[184:187], v[112:115]
	v_mfma_f32_16x16x32_bf16 v[112:115], v[172:175], v[188:191], v[112:115]
	v_mfma_f32_16x16x32_bf16 v[104:107], v[180:183], v[188:191], v[104:107]
	v_mfma_f32_16x16x32_bf16 v[104:107], v[176:179], v[184:187], v[104:107]
	v_mfma_f32_16x16x32_bf16 v[88:91], v[176:179], v[192:195], v[88:91]
	v_mfma_f32_16x16x32_bf16 v[88:91], v[180:183], v[196:199], v[88:91]
	v_mfma_f32_16x16x32_bf16 v[96:99], v[172:175], v[196:199], v[96:99]
	v_mfma_f32_16x16x32_bf16 v[96:99], v[168:171], v[192:195], v[96:99]
	v_mfma_f32_16x16x32_bf16 v[108:111], v[160:163], v[192:195], v[108:111]
	v_mfma_f32_16x16x32_bf16 v[108:111], v[164:167], v[196:199], v[108:111]
	v_mfma_f32_16x16x32_bf16 v[116:119], v[156:159], v[196:199], v[116:119]
	v_mfma_f32_16x16x32_bf16 v[116:119], v[144:147], v[192:195], v[116:119]
	v_mfma_f32_16x16x32_bf16 v[100:103], v[144:147], v[200:203], v[100:103]
	v_mfma_f32_16x16x32_bf16 v[100:103], v[156:159], v[204:207], v[100:103]
	v_mfma_f32_16x16x32_bf16 v[92:95], v[164:167], v[204:207], v[92:95]
	v_mfma_f32_16x16x32_bf16 v[92:95], v[160:163], v[200:203], v[92:95]
	v_mfma_f32_16x16x32_bf16 v[80:83], v[168:171], v[200:203], v[80:83]
	v_mfma_f32_16x16x32_bf16 v[80:83], v[172:175], v[204:207], v[80:83]
	v_mfma_f32_16x16x32_bf16 v[72:75], v[180:183], v[204:207], v[72:75]
	v_mfma_f32_16x16x32_bf16 v[72:75], v[176:179], v[200:203], v[72:75]
	v_mfma_f32_16x16x32_bf16 v[64:67], v[176:179], v[208:211], v[64:67]
	v_mfma_f32_16x16x32_bf16 v[64:67], v[180:183], v[212:215], v[64:67]
	v_mfma_f32_16x16x32_bf16 v[68:71], v[172:175], v[212:215], v[68:71]
	v_mfma_f32_16x16x32_bf16 v[68:71], v[168:171], v[208:211], v[68:71]
	v_mfma_f32_16x16x32_bf16 v[76:79], v[160:163], v[208:211], v[76:79]
	v_mfma_f32_16x16x32_bf16 v[76:79], v[164:167], v[212:215], v[76:79]
	s_barrier
	s_setprio 3
	v_mfma_f32_16x16x32_bf16 v[84:87], v[156:159], v[212:215], v[84:87]
	v_mfma_f32_16x16x32_bf16 v[84:87], v[144:147], v[208:211], v[84:87]
	s_setprio 0
	s_add_i32 s24, s57, s41
	v_lshl_add_u64 v[184:185], v[216:217], 0, s[8:9]
	s_mov_b32 m0, s24
	s_nop 0
	global_load_lds_dwordx4 v[184:185], off
	s_add_i32 m0, s24, 0x2000
	s_add_u32 s24, s30, 0x100080
	v_lshl_add_u64 v[184:185], v[218:219], 0, s[8:9]
	s_addc_u32 s25, s31, 0
	s_add_i32 s30, s58, s41
	global_load_lds_dwordx4 v[184:185], off
	v_lshl_add_u64 v[184:185], s[24:25], 0, v[130:131]
	s_mov_b32 m0, s30
	s_nop 0
	global_load_lds_dwordx4 v[184:185], off
	v_lshl_add_u64 v[184:185], s[24:25], 0, v[134:135]
	s_add_i32 m0, s30, 0x2000
	s_nop 0
	global_load_lds_dwordx4 v[184:185], off
	v_lshl_add_u64 v[184:185], v[220:221], 0, s[8:9]
	s_mov_b32 m0, s46
	s_nop 0
	global_load_lds_dwordx4 v[184:185], off
	v_lshl_add_u64 v[184:185], v[222:223], 0, s[8:9]
	s_mov_b32 m0, s47
	s_nop 0
	global_load_lds_dwordx4 v[184:185], off
	ds_read_b128 v[184:187], v154 offset:49152
	ds_read_b128 v[188:191], v154 offset:50176
	ds_read_b128 v[192:195], v154 offset:51200
	ds_read_b128 v[196:199], v154 offset:52224
	ds_read_b128 v[200:203], v154 offset:53248
	ds_read_b128 v[204:207], v154 offset:54272
	ds_read_b128 v[208:211], v154 offset:55296
	ds_read_b128 v[212:215], v154 offset:56320
	s_waitcnt vmcnt(8)
	s_waitcnt lgkmcnt(0)
	s_barrier
	v_mfma_f32_16x16x32_bf16 v[60:63], v[144:147], v[184:187], v[60:63]
	v_mfma_f32_16x16x32_bf16 v[60:63], v[156:159], v[188:191], v[60:63]
	v_mfma_f32_16x16x32_bf16 v[56:59], v[164:167], v[188:191], v[56:59]
	v_mfma_f32_16x16x32_bf16 v[56:59], v[160:163], v[184:187], v[56:59]
	v_mfma_f32_16x16x32_bf16 v[48:51], v[168:171], v[184:187], v[48:51]
	v_mfma_f32_16x16x32_bf16 v[48:51], v[172:175], v[188:191], v[48:51]
	v_mfma_f32_16x16x32_bf16 v[40:43], v[180:183], v[188:191], v[40:43]
	v_mfma_f32_16x16x32_bf16 v[40:43], v[176:179], v[184:187], v[40:43]
	v_mfma_f32_16x16x32_bf16 v[24:27], v[176:179], v[192:195], v[24:27]
	v_mfma_f32_16x16x32_bf16 v[24:27], v[180:183], v[196:199], v[24:27]
	v_mfma_f32_16x16x32_bf16 v[32:35], v[172:175], v[196:199], v[32:35]
	v_mfma_f32_16x16x32_bf16 v[32:35], v[168:171], v[192:195], v[32:35]
	v_mfma_f32_16x16x32_bf16 v[44:47], v[160:163], v[192:195], v[44:47]
	v_mfma_f32_16x16x32_bf16 v[44:47], v[164:167], v[196:199], v[44:47]
	v_mfma_f32_16x16x32_bf16 v[52:55], v[156:159], v[196:199], v[52:55]
	v_mfma_f32_16x16x32_bf16 v[52:55], v[144:147], v[192:195], v[52:55]
	v_mfma_f32_16x16x32_bf16 v[36:39], v[144:147], v[200:203], v[36:39]
	v_mfma_f32_16x16x32_bf16 v[36:39], v[156:159], v[204:207], v[36:39]
	v_mfma_f32_16x16x32_bf16 v[28:31], v[164:167], v[204:207], v[28:31]
	v_mfma_f32_16x16x32_bf16 v[28:31], v[160:163], v[200:203], v[28:31]
	v_mfma_f32_16x16x32_bf16 v[16:19], v[168:171], v[200:203], v[16:19]
	v_mfma_f32_16x16x32_bf16 v[16:19], v[172:175], v[204:207], v[16:19]
	v_mfma_f32_16x16x32_bf16 v[8:11], v[180:183], v[204:207], v[8:11]
	v_mfma_f32_16x16x32_bf16 v[8:11], v[176:179], v[200:203], v[8:11]
	v_mfma_f32_16x16x32_bf16 v[0:3], v[176:179], v[208:211], v[0:3]
	v_mfma_f32_16x16x32_bf16 v[0:3], v[180:183], v[212:215], v[0:3]
	v_mfma_f32_16x16x32_bf16 v[4:7], v[172:175], v[212:215], v[4:7]
	v_mfma_f32_16x16x32_bf16 v[4:7], v[168:171], v[208:211], v[4:7]
	v_mfma_f32_16x16x32_bf16 v[12:15], v[160:163], v[208:211], v[12:15]
	v_mfma_f32_16x16x32_bf16 v[12:15], v[164:167], v[212:215], v[12:15]
	s_barrier
	s_setprio 3
	v_mfma_f32_16x16x32_bf16 v[20:23], v[156:159], v[212:215], v[20:23]
	v_mfma_f32_16x16x32_bf16 v[20:23], v[144:147], v[208:211], v[20:23]
	s_setprio 0
	s_add_i32 s56, s56, 2
	s_add_u32 s54, s54, 0x100
	s_addc_u32 s55, s55, 0
	s_cmp_gt_u32 s56, 61
	s_mov_b64 s[24:25], s[28:29]
	s_cbranch_scc0 .LBB0_333
	s_and_b64 vcc, exec, s[0:1]
	s_cbranch_vccz .LBB0_336
	s_barrier

.LBB0_1202:
	ds_read_b128 v[128:131], v176
	ds_read_b128 v[132:135], v176 offset:1024
	ds_read_b128 v[136:139], v176 offset:2048
	ds_read_b128 v[140:143], v176 offset:3072
	ds_read_b128 v[144:147], v177
	ds_read_b128 v[148:151], v177 offset:1024
	ds_read_b128 v[180:183], v177 offset:2048
	ds_read_b128 v[184:187], v177 offset:3072
	s_add_u32 s30, s28, 0xfff00080
	s_addc_u32 s31, s29, -1
	s_cmp_eq_u32 s40, 60
	s_cselect_b32 s35, s23, s31
	s_cselect_b32 s34, s36, s30
	s_cselect_b32 s31, s21, s39
	s_cselect_b32 s30, s37, s38
	v_lshl_add_u64 v[172:173], s[28:29], 0, v[164:165]
	s_add_i32 m0, s7, 0xc000
	s_nop 0
	global_load_lds_dwordx4 v[172:173], off
	v_lshl_add_u64 v[172:173], s[28:29], 0, v[166:167]
	s_add_i32 m0, s7, 0xe000
	s_nop 0
	global_load_lds_dwordx4 v[172:173], off
	ds_read_b128 v[188:191], v178
	ds_read_b128 v[192:195], v178 offset:1024
	ds_read_b128 v[196:199], v178 offset:2048
	ds_read_b128 v[200:203], v178 offset:3072
	ds_read_b128 v[204:207], v178 offset:4096
	ds_read_b128 v[208:211], v178 offset:5120
	ds_read_b128 v[212:215], v178 offset:6144
	ds_read_b128 v[216:219], v178 offset:7168
	s_waitcnt vmcnt(8)
	s_waitcnt lgkmcnt(0)
	s_barrier
	v_mfma_f32_16x16x32_bf16 v[124:127], v[128:131], v[188:191], v[124:127]
	v_mfma_f32_16x16x32_bf16 v[124:127], v[132:135], v[192:195], v[124:127]
	v_mfma_f32_16x16x32_bf16 v[120:123], v[140:143], v[192:195], v[120:123]
	v_mfma_f32_16x16x32_bf16 v[120:123], v[136:139], v[188:191], v[120:123]
	v_mfma_f32_16x16x32_bf16 v[116:119], v[144:147], v[188:191], v[116:119]
	v_mfma_f32_16x16x32_bf16 v[116:119], v[148:151], v[192:195], v[116:119]
	v_mfma_f32_16x16x32_bf16 v[112:115], v[184:187], v[192:195], v[112:115]
	v_mfma_f32_16x16x32_bf16 v[112:115], v[180:183], v[188:191], v[112:115]
	v_mfma_f32_16x16x32_bf16 v[96:99], v[180:183], v[196:199], v[96:99]
	v_mfma_f32_16x16x32_bf16 v[96:99], v[184:187], v[200:203], v[96:99]
	v_mfma_f32_16x16x32_bf16 v[100:103], v[148:151], v[200:203], v[100:103]
	v_mfma_f32_16x16x32_bf16 v[100:103], v[144:147], v[196:199], v[100:103]
	v_mfma_f32_16x16x32_bf16 v[104:107], v[136:139], v[196:199], v[104:107]
	v_mfma_f32_16x16x32_bf16 v[104:107], v[140:143], v[200:203], v[104:107]
	v_mfma_f32_16x16x32_bf16 v[108:111], v[132:135], v[200:203], v[108:111]
	v_mfma_f32_16x16x32_bf16 v[108:111], v[128:131], v[196:199], v[108:111]
	v_mfma_f32_16x16x32_bf16 v[92:95], v[128:131], v[204:207], v[92:95]
	v_mfma_f32_16x16x32_bf16 v[92:95], v[132:135], v[208:211], v[92:95]
	v_mfma_f32_16x16x32_bf16 v[88:91], v[140:143], v[208:211], v[88:91]
	v_mfma_f32_16x16x32_bf16 v[88:91], v[136:139], v[204:207], v[88:91]
	v_mfma_f32_16x16x32_bf16 v[84:87], v[144:147], v[204:207], v[84:87]
	v_mfma_f32_16x16x32_bf16 v[84:87], v[148:151], v[208:211], v[84:87]
	v_mfma_f32_16x16x32_bf16 v[80:83], v[184:187], v[208:211], v[80:83]
	v_mfma_f32_16x16x32_bf16 v[80:83], v[180:183], v[204:207], v[80:83]
	v_mfma_f32_16x16x32_bf16 v[64:67], v[180:183], v[212:215], v[64:67]
	v_mfma_f32_16x16x32_bf16 v[64:67], v[184:187], v[216:219], v[64:67]
	v_mfma_f32_16x16x32_bf16 v[68:71], v[148:151], v[216:219], v[68:71]
	v_mfma_f32_16x16x32_bf16 v[68:71], v[144:147], v[212:215], v[68:71]
	v_mfma_f32_16x16x32_bf16 v[72:75], v[136:139], v[212:215], v[72:75]
	v_mfma_f32_16x16x32_bf16 v[72:75], v[140:143], v[216:219], v[72:75]
	s_barrier
	s_setprio 3
	v_mfma_f32_16x16x32_bf16 v[76:79], v[132:135], v[216:219], v[76:79]
	v_mfma_f32_16x16x32_bf16 v[76:79], v[128:131], v[212:215], v[76:79]
	s_setprio 0
	s_add_i32 s41, s68, s33
	v_lshl_add_u64 v[172:173], s[30:31], 0, v[154:155]
	s_mov_b32 m0, s41
	v_lshl_add_u64 v[220:221], s[30:31], 0, v[158:159]
	global_load_lds_dwordx4 v[172:173], off
	s_add_i32 m0, s41, 0x2000
	s_add_u32 s42, s30, 0x100000
	s_addc_u32 s43, s31, 0
	s_add_i32 s41, s69, s33
	global_load_lds_dwordx4 v[220:221], off
	v_lshl_add_u64 v[188:189], s[42:43], 0, v[154:155]
	s_mov_b32 m0, s41
	v_lshl_add_u64 v[222:223], s[34:35], 0, v[152:153]
	global_load_lds_dwordx4 v[188:189], off
	v_lshl_add_u64 v[188:189], s[42:43], 0, v[158:159]
	s_add_i32 m0, s41, 0x2000
	v_lshl_add_u64 v[224:225], s[34:35], 0, v[156:157]
	global_load_lds_dwordx4 v[188:189], off
	s_mov_b32 m0, s7
	s_nop 0
	global_load_lds_dwordx4 v[222:223], off
	s_mov_b32 m0, s59
	s_nop 0
	global_load_lds_dwordx4 v[224:225], off
	ds_read_b128 v[188:191], v178 offset:16384
	ds_read_b128 v[192:195], v178 offset:17408
	ds_read_b128 v[196:199], v178 offset:18432
	ds_read_b128 v[200:203], v178 offset:19456
	ds_read_b128 v[204:207], v178 offset:20480
	ds_read_b128 v[208:211], v178 offset:21504
	ds_read_b128 v[212:215], v178 offset:22528
	ds_read_b128 v[216:219], v178 offset:23552
	s_waitcnt vmcnt(8)
	s_waitcnt lgkmcnt(0)
	s_barrier
	v_mfma_f32_16x16x32_bf16 v[60:63], v[128:131], v[188:191], v[60:63]
	v_mfma_f32_16x16x32_bf16 v[60:63], v[132:135], v[192:195], v[60:63]
	v_mfma_f32_16x16x32_bf16 v[56:59], v[140:143], v[192:195], v[56:59]
	v_mfma_f32_16x16x32_bf16 v[56:59], v[136:139], v[188:191], v[56:59]
	v_mfma_f32_16x16x32_bf16 v[52:55], v[144:147], v[188:191], v[52:55]
	v_mfma_f32_16x16x32_bf16 v[52:55], v[148:151], v[192:195], v[52:55]
	v_mfma_f32_16x16x32_bf16 v[48:51], v[184:187], v[192:195], v[48:51]
	v_mfma_f32_16x16x32_bf16 v[48:51], v[180:183], v[188:191], v[48:51]
	v_mfma_f32_16x16x32_bf16 v[32:35], v[180:183], v[196:199], v[32:35]
	v_mfma_f32_16x16x32_bf16 v[32:35], v[184:187], v[200:203], v[32:35]
	v_mfma_f32_16x16x32_bf16 v[36:39], v[148:151], v[200:203], v[36:39]
	v_mfma_f32_16x16x32_bf16 v[36:39], v[144:147], v[196:199], v[36:39]
	v_mfma_f32_16x16x32_bf16 v[40:43], v[136:139], v[196:199], v[40:43]
	v_mfma_f32_16x16x32_bf16 v[40:43], v[140:143], v[200:203], v[40:43]
	v_mfma_f32_16x16x32_bf16 v[44:47], v[132:135], v[200:203], v[44:47]
	v_mfma_f32_16x16x32_bf16 v[44:47], v[128:131], v[196:199], v[44:47]
	v_mfma_f32_16x16x32_bf16 v[28:31], v[128:131], v[204:207], v[28:31]
	v_mfma_f32_16x16x32_bf16 v[28:31], v[132:135], v[208:211], v[28:31]
	v_mfma_f32_16x16x32_bf16 v[24:27], v[140:143], v[208:211], v[24:27]
	v_mfma_f32_16x16x32_bf16 v[24:27], v[136:139], v[204:207], v[24:27]
	v_mfma_f32_16x16x32_bf16 v[20:23], v[144:147], v[204:207], v[20:23]
	v_mfma_f32_16x16x32_bf16 v[20:23], v[148:151], v[208:211], v[20:23]
	v_mfma_f32_16x16x32_bf16 v[16:19], v[184:187], v[208:211], v[16:19]
	v_mfma_f32_16x16x32_bf16 v[16:19], v[180:183], v[204:207], v[16:19]
	v_mfma_f32_16x16x32_bf16 v[0:3], v[180:183], v[212:215], v[0:3]
	v_mfma_f32_16x16x32_bf16 v[0:3], v[184:187], v[216:219], v[0:3]
	v_mfma_f32_16x16x32_bf16 v[4:7], v[148:151], v[216:219], v[4:7]
	v_mfma_f32_16x16x32_bf16 v[4:7], v[144:147], v[212:215], v[4:7]
	v_mfma_f32_16x16x32_bf16 v[8:11], v[136:139], v[212:215], v[8:11]
	v_mfma_f32_16x16x32_bf16 v[8:11], v[140:143], v[216:219], v[8:11]
	s_barrier
	s_setprio 3
	v_mfma_f32_16x16x32_bf16 v[12:15], v[132:135], v[216:219], v[12:15]
	v_mfma_f32_16x16x32_bf16 v[12:15], v[128:131], v[212:215], v[12:15]
	s_setprio 0
	s_add_i32 s41, 0, 0x18000
	s_add_i32 s42, 0, 0x1c000
	v_add_u32_e32 v140, s41, v174
	v_add_u32_e32 v184, s42, v174
	ds_read_b128 v[128:131], v140
	ds_read_b128 v[132:135], v140 offset:1024
	ds_read_b128 v[136:139], v140 offset:2048
	ds_read_b128 v[140:143], v140 offset:3072
	ds_read_b128 v[144:147], v184
	ds_read_b128 v[148:151], v184 offset:1024
	ds_read_b128 v[180:183], v184 offset:2048
	ds_read_b128 v[184:187], v184 offset:3072
	s_add_u32 s34, s34, 0x100000
	s_addc_u32 s35, s35, 0
	s_mov_b32 m0, s60
	v_lshl_add_u64 v[188:189], s[34:35], 0, v[152:153]
	global_load_lds_dwordx4 v[188:189], off
	v_lshl_add_u64 v[188:189], s[34:35], 0, v[156:157]
	s_mov_b32 m0, s61
	s_nop 0
	global_load_lds_dwordx4 v[188:189], off
	ds_read_b128 v[188:191], v178 offset:32768
	ds_read_b128 v[192:195], v178 offset:33792
	ds_read_b128 v[196:199], v178 offset:34816
	ds_read_b128 v[200:203], v178 offset:35840
	ds_read_b128 v[204:207], v178 offset:36864
	ds_read_b128 v[208:211], v178 offset:37888
	ds_read_b128 v[212:215], v178 offset:38912
	ds_read_b128 v[216:219], v178 offset:39936
	s_waitcnt vmcnt(8)
	s_waitcnt lgkmcnt(0)
	s_barrier
	v_mfma_f32_16x16x32_bf16 v[124:127], v[128:131], v[188:191], v[124:127]
	v_mfma_f32_16x16x32_bf16 v[124:127], v[132:135], v[192:195], v[124:127]
	v_mfma_f32_16x16x32_bf16 v[120:123], v[140:143], v[192:195], v[120:123]
	v_mfma_f32_16x16x32_bf16 v[120:123], v[136:139], v[188:191], v[120:123]
	v_mfma_f32_16x16x32_bf16 v[116:119], v[144:147], v[188:191], v[116:119]
	v_mfma_f32_16x16x32_bf16 v[116:119], v[148:151], v[192:195], v[116:119]
	v_mfma_f32_16x16x32_bf16 v[112:115], v[184:187], v[192:195], v[112:115]
	v_mfma_f32_16x16x32_bf16 v[112:115], v[180:183], v[188:191], v[112:115]
	v_mfma_f32_16x16x32_bf16 v[96:99], v[180:183], v[196:199], v[96:99]
	v_mfma_f32_16x16x32_bf16 v[96:99], v[184:187], v[200:203], v[96:99]
	v_mfma_f32_16x16x32_bf16 v[100:103], v[148:151], v[200:203], v[100:103]
	v_mfma_f32_16x16x32_bf16 v[100:103], v[144:147], v[196:199], v[100:103]
	v_mfma_f32_16x16x32_bf16 v[104:107], v[136:139], v[196:199], v[104:107]
	v_mfma_f32_16x16x32_bf16 v[104:107], v[140:143], v[200:203], v[104:107]
	v_mfma_f32_16x16x32_bf16 v[108:111], v[132:135], v[200:203], v[108:111]
	v_mfma_f32_16x16x32_bf16 v[108:111], v[128:131], v[196:199], v[108:111]
	v_mfma_f32_16x16x32_bf16 v[92:95], v[128:131], v[204:207], v[92:95]
	v_mfma_f32_16x16x32_bf16 v[92:95], v[132:135], v[208:211], v[92:95]
	v_mfma_f32_16x16x32_bf16 v[88:91], v[140:143], v[208:211], v[88:91]
	v_mfma_f32_16x16x32_bf16 v[88:91], v[136:139], v[204:207], v[88:91]
	v_mfma_f32_16x16x32_bf16 v[84:87], v[144:147], v[204:207], v[84:87]
	v_mfma_f32_16x16x32_bf16 v[84:87], v[148:151], v[208:211], v[84:87]
	v_mfma_f32_16x16x32_bf16 v[80:83], v[184:187], v[208:211], v[80:83]
	v_mfma_f32_16x16x32_bf16 v[80:83], v[180:183], v[204:207], v[80:83]
	v_mfma_f32_16x16x32_bf16 v[64:67], v[180:183], v[212:215], v[64:67]
	v_mfma_f32_16x16x32_bf16 v[64:67], v[184:187], v[216:219], v[64:67]
	v_mfma_f32_16x16x32_bf16 v[68:71], v[148:151], v[216:219], v[68:71]
	v_mfma_f32_16x16x32_bf16 v[68:71], v[144:147], v[212:215], v[68:71]
	v_mfma_f32_16x16x32_bf16 v[72:75], v[136:139], v[212:215], v[72:75]
	v_mfma_f32_16x16x32_bf16 v[72:75], v[140:143], v[216:219], v[72:75]
	s_barrier
	s_setprio 3
	v_mfma_f32_16x16x32_bf16 v[76:79], v[132:135], v[216:219], v[76:79]
	v_mfma_f32_16x16x32_bf16 v[76:79], v[128:131], v[212:215], v[76:79]
	s_setprio 0
	s_add_i32 s34, s41, s33
	v_lshl_add_u64 v[172:173], v[172:173], 0, s[16:17]
	s_mov_b32 m0, s34
	s_nop 0
	global_load_lds_dwordx4 v[172:173], off
	s_add_i32 m0, s34, 0x2000
	s_add_u32 s30, s30, 0x100800
	v_lshl_add_u64 v[172:173], v[220:221], 0, s[16:17]
	s_addc_u32 s31, s31, 0
	s_add_i32 s34, s42, s33
	global_load_lds_dwordx4 v[172:173], off
	v_lshl_add_u64 v[172:173], s[30:31], 0, v[154:155]
	s_mov_b32 m0, s34
	s_nop 0
	global_load_lds_dwordx4 v[172:173], off
	v_lshl_add_u64 v[172:173], s[30:31], 0, v[158:159]
	s_add_i32 m0, s34, 0x2000
	s_nop 0
	global_load_lds_dwordx4 v[172:173], off
	v_lshl_add_u64 v[172:173], v[222:223], 0, s[18:19]
	s_mov_b32 m0, s63
	s_nop 0
	global_load_lds_dwordx4 v[172:173], off
	v_lshl_add_u64 v[172:173], v[224:225], 0, s[18:19]
	s_mov_b32 m0, s64
	s_nop 0
	global_load_lds_dwordx4 v[172:173], off
	ds_read_b128 v[188:191], v178 offset:49152
	ds_read_b128 v[192:195], v178 offset:50176
	ds_read_b128 v[196:199], v178 offset:51200
	ds_read_b128 v[200:203], v178 offset:52224
	ds_read_b128 v[204:207], v178 offset:53248
	ds_read_b128 v[208:211], v178 offset:54272
	ds_read_b128 v[212:215], v178 offset:55296
	ds_read_b128 v[216:219], v178 offset:56320
	s_waitcnt vmcnt(8)
	s_waitcnt lgkmcnt(0)
	s_barrier
	v_mfma_f32_16x16x32_bf16 v[60:63], v[128:131], v[188:191], v[60:63]
	v_mfma_f32_16x16x32_bf16 v[60:63], v[132:135], v[192:195], v[60:63]
	v_mfma_f32_16x16x32_bf16 v[56:59], v[140:143], v[192:195], v[56:59]
	v_mfma_f32_16x16x32_bf16 v[56:59], v[136:139], v[188:191], v[56:59]
	v_mfma_f32_16x16x32_bf16 v[52:55], v[144:147], v[188:191], v[52:55]
	v_mfma_f32_16x16x32_bf16 v[52:55], v[148:151], v[192:195], v[52:55]
	v_mfma_f32_16x16x32_bf16 v[48:51], v[184:187], v[192:195], v[48:51]
	v_mfma_f32_16x16x32_bf16 v[48:51], v[180:183], v[188:191], v[48:51]
	v_mfma_f32_16x16x32_bf16 v[32:35], v[180:183], v[196:199], v[32:35]
	v_mfma_f32_16x16x32_bf16 v[32:35], v[184:187], v[200:203], v[32:35]
	v_mfma_f32_16x16x32_bf16 v[36:39], v[148:151], v[200:203], v[36:39]
	v_mfma_f32_16x16x32_bf16 v[36:39], v[144:147], v[196:199], v[36:39]
	v_mfma_f32_16x16x32_bf16 v[40:43], v[136:139], v[196:199], v[40:43]
	v_mfma_f32_16x16x32_bf16 v[40:43], v[140:143], v[200:203], v[40:43]
	v_mfma_f32_16x16x32_bf16 v[44:47], v[132:135], v[200:203], v[44:47]
	v_mfma_f32_16x16x32_bf16 v[44:47], v[128:131], v[196:199], v[44:47]
	v_mfma_f32_16x16x32_bf16 v[28:31], v[128:131], v[204:207], v[28:31]
	v_mfma_f32_16x16x32_bf16 v[28:31], v[132:135], v[208:211], v[28:31]
	v_mfma_f32_16x16x32_bf16 v[24:27], v[140:143], v[208:211], v[24:27]
	v_mfma_f32_16x16x32_bf16 v[24:27], v[136:139], v[204:207], v[24:27]
	v_mfma_f32_16x16x32_bf16 v[20:23], v[144:147], v[204:207], v[20:23]
	v_mfma_f32_16x16x32_bf16 v[20:23], v[148:151], v[208:211], v[20:23]
	v_mfma_f32_16x16x32_bf16 v[16:19], v[184:187], v[208:211], v[16:19]
	v_mfma_f32_16x16x32_bf16 v[16:19], v[180:183], v[204:207], v[16:19]
	v_mfma_f32_16x16x32_bf16 v[0:3], v[180:183], v[212:215], v[0:3]
	v_mfma_f32_16x16x32_bf16 v[0:3], v[184:187], v[216:219], v[0:3]
	v_mfma_f32_16x16x32_bf16 v[4:7], v[148:151], v[216:219], v[4:7]
	v_mfma_f32_16x16x32_bf16 v[4:7], v[144:147], v[212:215], v[4:7]
	v_mfma_f32_16x16x32_bf16 v[8:11], v[136:139], v[212:215], v[8:11]
	v_mfma_f32_16x16x32_bf16 v[8:11], v[140:143], v[216:219], v[8:11]
	s_barrier
	s_setprio 3
	v_mfma_f32_16x16x32_bf16 v[12:15], v[132:135], v[216:219], v[12:15]
	v_mfma_f32_16x16x32_bf16 v[12:15], v[128:131], v[212:215], v[12:15]
	s_setprio 0
	s_add_i32 s40, s40, 2
	s_add_u32 s38, s38, 0x1000
	s_addc_u32 s39, s39, 0
	s_add_u32 s28, s28, 0x100
	s_addc_u32 s29, s29, 0
	s_cmp_gt_u32 s40, 61
	s_cbranch_scc0 .LBB0_1202

.LBB0_1263:
	ds_read_b128 v[146:149], v152
	ds_read_b128 v[156:159], v152 offset:1024
	ds_read_b128 v[160:163], v152 offset:2048
	ds_read_b128 v[164:167], v152 offset:3072
	ds_read_b128 v[168:171], v153
	ds_read_b128 v[172:175], v153 offset:1024
	ds_read_b128 v[176:179], v153 offset:2048
	ds_read_b128 v[180:183], v153 offset:3072
	s_add_u32 s22, s20, 0x100
	s_addc_u32 s23, s21, 0
	s_cmp_eq_u32 s46, 12
	s_cselect_b32 s27, s5, s23
	s_cselect_b32 s26, s4, s22
	s_cselect_b32 s25, s19, s15
	s_cselect_b32 s24, s18, s6
	v_lshl_add_u64 v[184:185], s[20:21], 0, v[136:137]
	s_add_i32 m0, s17, 0xc000
	s_nop 0
	global_load_lds_dwordx4 v[184:185], off
	v_lshl_add_u64 v[184:185], s[20:21], 0, v[138:139]
	s_add_i32 m0, s17, 0xe000
	s_nop 0
	global_load_lds_dwordx4 v[184:185], off
	ds_read_b128 v[184:187], v154
	ds_read_b128 v[188:191], v154 offset:1024
	ds_read_b128 v[192:195], v154 offset:2048
	ds_read_b128 v[196:199], v154 offset:3072
	ds_read_b128 v[200:203], v154 offset:4096
	ds_read_b128 v[204:207], v154 offset:5120
	ds_read_b128 v[208:211], v154 offset:6144
	ds_read_b128 v[212:215], v154 offset:7168
	s_waitcnt vmcnt(8)
	s_waitcnt lgkmcnt(0)
	s_barrier
	v_mfma_f32_16x16x32_bf16 v[124:127], v[146:149], v[184:187], v[124:127]
	v_mfma_f32_16x16x32_bf16 v[124:127], v[156:159], v[188:191], v[124:127]
	v_mfma_f32_16x16x32_bf16 v[120:123], v[164:167], v[188:191], v[120:123]
	v_mfma_f32_16x16x32_bf16 v[120:123], v[160:163], v[184:187], v[120:123]
	v_mfma_f32_16x16x32_bf16 v[116:119], v[168:171], v[184:187], v[116:119]
	v_mfma_f32_16x16x32_bf16 v[116:119], v[172:175], v[188:191], v[116:119]
	v_mfma_f32_16x16x32_bf16 v[108:111], v[180:183], v[188:191], v[108:111]
	v_mfma_f32_16x16x32_bf16 v[108:111], v[176:179], v[184:187], v[108:111]
	v_mfma_f32_16x16x32_bf16 v[92:95], v[176:179], v[192:195], v[92:95]
	v_mfma_f32_16x16x32_bf16 v[92:95], v[180:183], v[196:199], v[92:95]
	v_mfma_f32_16x16x32_bf16 v[100:103], v[172:175], v[196:199], v[100:103]
	v_mfma_f32_16x16x32_bf16 v[100:103], v[168:171], v[192:195], v[100:103]
	v_mfma_f32_16x16x32_bf16 v[104:107], v[160:163], v[192:195], v[104:107]
	v_mfma_f32_16x16x32_bf16 v[104:107], v[164:167], v[196:199], v[104:107]
	v_mfma_f32_16x16x32_bf16 v[112:115], v[156:159], v[196:199], v[112:115]
	v_mfma_f32_16x16x32_bf16 v[112:115], v[146:149], v[192:195], v[112:115]
	v_mfma_f32_16x16x32_bf16 v[96:99], v[146:149], v[200:203], v[96:99]
	v_mfma_f32_16x16x32_bf16 v[96:99], v[156:159], v[204:207], v[96:99]
	v_mfma_f32_16x16x32_bf16 v[88:91], v[164:167], v[204:207], v[88:91]
	v_mfma_f32_16x16x32_bf16 v[88:91], v[160:163], v[200:203], v[88:91]
	v_mfma_f32_16x16x32_bf16 v[84:87], v[168:171], v[200:203], v[84:87]
	v_mfma_f32_16x16x32_bf16 v[84:87], v[172:175], v[204:207], v[84:87]
	v_mfma_f32_16x16x32_bf16 v[76:79], v[180:183], v[204:207], v[76:79]
	v_mfma_f32_16x16x32_bf16 v[76:79], v[176:179], v[200:203], v[76:79]
	v_mfma_f32_16x16x32_bf16 v[64:67], v[176:179], v[208:211], v[64:67]
	v_mfma_f32_16x16x32_bf16 v[64:67], v[180:183], v[212:215], v[64:67]
	v_mfma_f32_16x16x32_bf16 v[68:71], v[172:175], v[212:215], v[68:71]
	v_mfma_f32_16x16x32_bf16 v[68:71], v[168:171], v[208:211], v[68:71]
	v_mfma_f32_16x16x32_bf16 v[72:75], v[160:163], v[208:211], v[72:75]
	v_mfma_f32_16x16x32_bf16 v[72:75], v[164:167], v[212:215], v[72:75]
	s_barrier
	s_setprio 3
	v_mfma_f32_16x16x32_bf16 v[80:83], v[156:159], v[212:215], v[80:83]
	v_mfma_f32_16x16x32_bf16 v[80:83], v[146:149], v[208:211], v[80:83]
	s_setprio 0
	s_add_i32 s20, s41, s33
	v_lshl_add_u64 v[216:217], s[24:25], 0, v[130:131]
	s_mov_b32 m0, s20
	v_lshl_add_u64 v[218:219], s[24:25], 0, v[134:135]
	global_load_lds_dwordx4 v[216:217], off
	s_add_i32 m0, s20, 0x2000
	s_add_u32 s20, s24, 0x200000
	s_addc_u32 s21, s25, 0
	s_add_i32 s47, s42, s33
	global_load_lds_dwordx4 v[218:219], off
	v_lshl_add_u64 v[184:185], s[20:21], 0, v[130:131]
	s_mov_b32 m0, s47
	v_lshl_add_u64 v[220:221], s[26:27], 0, v[128:129]
	global_load_lds_dwordx4 v[184:185], off
	v_lshl_add_u64 v[184:185], s[20:21], 0, v[134:135]
	s_add_i32 m0, s47, 0x2000
	v_lshl_add_u64 v[222:223], s[26:27], 0, v[132:133]
	global_load_lds_dwordx4 v[184:185], off
	s_mov_b32 m0, s17
	s_nop 0
	global_load_lds_dwordx4 v[220:221], off
	s_mov_b32 m0, s34
	s_nop 0
	global_load_lds_dwordx4 v[222:223], off
	ds_read_b128 v[184:187], v154 offset:16384
	ds_read_b128 v[188:191], v154 offset:17408
	ds_read_b128 v[192:195], v154 offset:18432
	ds_read_b128 v[196:199], v154 offset:19456
	ds_read_b128 v[200:203], v154 offset:20480
	ds_read_b128 v[204:207], v154 offset:21504
	ds_read_b128 v[208:211], v154 offset:22528
	ds_read_b128 v[212:215], v154 offset:23552
	s_waitcnt vmcnt(8)
	s_waitcnt lgkmcnt(0)
	s_barrier
	v_mfma_f32_16x16x32_bf16 v[60:63], v[146:149], v[184:187], v[60:63]
	v_mfma_f32_16x16x32_bf16 v[60:63], v[156:159], v[188:191], v[60:63]
	v_mfma_f32_16x16x32_bf16 v[56:59], v[164:167], v[188:191], v[56:59]
	v_mfma_f32_16x16x32_bf16 v[56:59], v[160:163], v[184:187], v[56:59]
	v_mfma_f32_16x16x32_bf16 v[52:55], v[168:171], v[184:187], v[52:55]
	v_mfma_f32_16x16x32_bf16 v[52:55], v[172:175], v[188:191], v[52:55]
	v_mfma_f32_16x16x32_bf16 v[44:47], v[180:183], v[188:191], v[44:47]
	v_mfma_f32_16x16x32_bf16 v[44:47], v[176:179], v[184:187], v[44:47]
	v_mfma_f32_16x16x32_bf16 v[28:31], v[176:179], v[192:195], v[28:31]
	v_mfma_f32_16x16x32_bf16 v[28:31], v[180:183], v[196:199], v[28:31]
	v_mfma_f32_16x16x32_bf16 v[36:39], v[172:175], v[196:199], v[36:39]
	v_mfma_f32_16x16x32_bf16 v[36:39], v[168:171], v[192:195], v[36:39]
	v_mfma_f32_16x16x32_bf16 v[40:43], v[160:163], v[192:195], v[40:43]
	v_mfma_f32_16x16x32_bf16 v[40:43], v[164:167], v[196:199], v[40:43]
	v_mfma_f32_16x16x32_bf16 v[48:51], v[156:159], v[196:199], v[48:51]
	v_mfma_f32_16x16x32_bf16 v[48:51], v[146:149], v[192:195], v[48:51]
	v_mfma_f32_16x16x32_bf16 v[32:35], v[146:149], v[200:203], v[32:35]
	v_mfma_f32_16x16x32_bf16 v[32:35], v[156:159], v[204:207], v[32:35]
	v_mfma_f32_16x16x32_bf16 v[24:27], v[164:167], v[204:207], v[24:27]
	v_mfma_f32_16x16x32_bf16 v[24:27], v[160:163], v[200:203], v[24:27]
	v_mfma_f32_16x16x32_bf16 v[20:23], v[168:171], v[200:203], v[20:23]
	v_mfma_f32_16x16x32_bf16 v[20:23], v[172:175], v[204:207], v[20:23]
	v_mfma_f32_16x16x32_bf16 v[12:15], v[180:183], v[204:207], v[12:15]
	v_mfma_f32_16x16x32_bf16 v[12:15], v[176:179], v[200:203], v[12:15]
	v_mfma_f32_16x16x32_bf16 v[0:3], v[176:179], v[208:211], v[0:3]
	v_mfma_f32_16x16x32_bf16 v[0:3], v[180:183], v[212:215], v[0:3]
	v_mfma_f32_16x16x32_bf16 v[4:7], v[172:175], v[212:215], v[4:7]
	v_mfma_f32_16x16x32_bf16 v[4:7], v[168:171], v[208:211], v[4:7]
	v_mfma_f32_16x16x32_bf16 v[8:11], v[160:163], v[208:211], v[8:11]
	v_mfma_f32_16x16x32_bf16 v[8:11], v[164:167], v[212:215], v[8:11]
	s_barrier
	s_setprio 3
	v_mfma_f32_16x16x32_bf16 v[16:19], v[156:159], v[212:215], v[16:19]
	v_mfma_f32_16x16x32_bf16 v[16:19], v[146:149], v[208:211], v[16:19]
	s_setprio 0
	s_add_i32 s47, 0, 0x18000
	v_add_u32_e32 v144, s47, v145
	s_add_i32 s48, 0, 0x1c000
	ds_read_b128 v[146:149], v144
	ds_read_b128 v[156:159], v144 offset:1024
	ds_read_b128 v[160:163], v144 offset:2048
	ds_read_b128 v[164:167], v144 offset:3072
	v_add_u32_e32 v144, s48, v145
	ds_read_b128 v[168:171], v144
	ds_read_b128 v[172:175], v144 offset:1024
	ds_read_b128 v[176:179], v144 offset:2048
	ds_read_b128 v[180:183], v144 offset:3072
	s_add_u32 s20, s26, 0x200000
	s_addc_u32 s21, s27, 0
	s_mov_b32 m0, s35
	v_lshl_add_u64 v[184:185], s[20:21], 0, v[128:129]
	global_load_lds_dwordx4 v[184:185], off
	v_lshl_add_u64 v[184:185], s[20:21], 0, v[132:133]
	s_mov_b32 m0, s36
	s_nop 0
	global_load_lds_dwordx4 v[184:185], off
	ds_read_b128 v[184:187], v154 offset:32768
	ds_read_b128 v[188:191], v154 offset:33792
	ds_read_b128 v[192:195], v154 offset:34816
	ds_read_b128 v[196:199], v154 offset:35840
	ds_read_b128 v[200:203], v154 offset:36864
	ds_read_b128 v[204:207], v154 offset:37888
	ds_read_b128 v[208:211], v154 offset:38912
	ds_read_b128 v[212:215], v154 offset:39936
	s_waitcnt vmcnt(8)
	s_waitcnt lgkmcnt(0)
	s_barrier
	v_mfma_f32_16x16x32_bf16 v[124:127], v[146:149], v[184:187], v[124:127]
	v_mfma_f32_16x16x32_bf16 v[124:127], v[156:159], v[188:191], v[124:127]
	v_mfma_f32_16x16x32_bf16 v[120:123], v[164:167], v[188:191], v[120:123]
	v_mfma_f32_16x16x32_bf16 v[120:123], v[160:163], v[184:187], v[120:123]
	v_mfma_f32_16x16x32_bf16 v[116:119], v[168:171], v[184:187], v[116:119]
	v_mfma_f32_16x16x32_bf16 v[116:119], v[172:175], v[188:191], v[116:119]
	v_mfma_f32_16x16x32_bf16 v[108:111], v[180:183], v[188:191], v[108:111]
	v_mfma_f32_16x16x32_bf16 v[108:111], v[176:179], v[184:187], v[108:111]
	v_mfma_f32_16x16x32_bf16 v[92:95], v[176:179], v[192:195], v[92:95]
	v_mfma_f32_16x16x32_bf16 v[92:95], v[180:183], v[196:199], v[92:95]
	v_mfma_f32_16x16x32_bf16 v[100:103], v[172:175], v[196:199], v[100:103]
	v_mfma_f32_16x16x32_bf16 v[100:103], v[168:171], v[192:195], v[100:103]
	v_mfma_f32_16x16x32_bf16 v[104:107], v[160:163], v[192:195], v[104:107]
	v_mfma_f32_16x16x32_bf16 v[104:107], v[164:167], v[196:199], v[104:107]
	v_mfma_f32_16x16x32_bf16 v[112:115], v[156:159], v[196:199], v[112:115]
	v_mfma_f32_16x16x32_bf16 v[112:115], v[146:149], v[192:195], v[112:115]
	v_mfma_f32_16x16x32_bf16 v[96:99], v[146:149], v[200:203], v[96:99]
	v_mfma_f32_16x16x32_bf16 v[96:99], v[156:159], v[204:207], v[96:99]
	v_mfma_f32_16x16x32_bf16 v[88:91], v[164:167], v[204:207], v[88:91]
	v_mfma_f32_16x16x32_bf16 v[88:91], v[160:163], v[200:203], v[88:91]
	v_mfma_f32_16x16x32_bf16 v[84:87], v[168:171], v[200:203], v[84:87]
	v_mfma_f32_16x16x32_bf16 v[84:87], v[172:175], v[204:207], v[84:87]
	v_mfma_f32_16x16x32_bf16 v[76:79], v[180:183], v[204:207], v[76:79]
	v_mfma_f32_16x16x32_bf16 v[76:79], v[176:179], v[200:203], v[76:79]
	v_mfma_f32_16x16x32_bf16 v[64:67], v[176:179], v[208:211], v[64:67]
	v_mfma_f32_16x16x32_bf16 v[64:67], v[180:183], v[212:215], v[64:67]
	v_mfma_f32_16x16x32_bf16 v[68:71], v[172:175], v[212:215], v[68:71]
	v_mfma_f32_16x16x32_bf16 v[68:71], v[168:171], v[208:211], v[68:71]
	v_mfma_f32_16x16x32_bf16 v[72:75], v[160:163], v[208:211], v[72:75]
	v_mfma_f32_16x16x32_bf16 v[72:75], v[164:167], v[212:215], v[72:75]
	s_barrier
	s_setprio 3
	v_mfma_f32_16x16x32_bf16 v[80:83], v[156:159], v[212:215], v[80:83]
	v_mfma_f32_16x16x32_bf16 v[80:83], v[146:149], v[208:211], v[80:83]
	s_setprio 0
	s_add_i32 s20, s47, s33
	v_lshl_add_u64 v[184:185], v[216:217], 0, s[12:13]
	s_mov_b32 m0, s20
	s_nop 0
	global_load_lds_dwordx4 v[184:185], off
	s_add_i32 m0, s20, 0x2000
	s_add_u32 s20, s24, 0x200080
	v_lshl_add_u64 v[184:185], v[218:219], 0, s[12:13]
	s_addc_u32 s21, s25, 0
	s_add_i32 s24, s48, s33
	global_load_lds_dwordx4 v[184:185], off
	v_lshl_add_u64 v[184:185], s[20:21], 0, v[130:131]
	s_mov_b32 m0, s24
	s_nop 0
	global_load_lds_dwordx4 v[184:185], off
	v_lshl_add_u64 v[184:185], s[20:21], 0, v[134:135]
	s_add_i32 m0, s24, 0x2000
	s_nop 0
	global_load_lds_dwordx4 v[184:185], off
	v_lshl_add_u64 v[184:185], v[220:221], 0, s[12:13]
	s_mov_b32 m0, s37
	s_nop 0
	global_load_lds_dwordx4 v[184:185], off
	v_lshl_add_u64 v[184:185], v[222:223], 0, s[12:13]
	s_mov_b32 m0, s38
	s_nop 0
	global_load_lds_dwordx4 v[184:185], off
	ds_read_b128 v[184:187], v154 offset:49152
	ds_read_b128 v[188:191], v154 offset:50176
	ds_read_b128 v[192:195], v154 offset:51200
	ds_read_b128 v[196:199], v154 offset:52224
	ds_read_b128 v[200:203], v154 offset:53248
	ds_read_b128 v[204:207], v154 offset:54272
	ds_read_b128 v[208:211], v154 offset:55296
	ds_read_b128 v[212:215], v154 offset:56320
	s_waitcnt vmcnt(8)
	s_waitcnt lgkmcnt(0)
	s_barrier
	v_mfma_f32_16x16x32_bf16 v[60:63], v[146:149], v[184:187], v[60:63]
	v_mfma_f32_16x16x32_bf16 v[60:63], v[156:159], v[188:191], v[60:63]
	v_mfma_f32_16x16x32_bf16 v[56:59], v[164:167], v[188:191], v[56:59]
	v_mfma_f32_16x16x32_bf16 v[56:59], v[160:163], v[184:187], v[56:59]
	v_mfma_f32_16x16x32_bf16 v[52:55], v[168:171], v[184:187], v[52:55]
	v_mfma_f32_16x16x32_bf16 v[52:55], v[172:175], v[188:191], v[52:55]
	v_mfma_f32_16x16x32_bf16 v[44:47], v[180:183], v[188:191], v[44:47]
	v_mfma_f32_16x16x32_bf16 v[44:47], v[176:179], v[184:187], v[44:47]
	v_mfma_f32_16x16x32_bf16 v[28:31], v[176:179], v[192:195], v[28:31]
	v_mfma_f32_16x16x32_bf16 v[28:31], v[180:183], v[196:199], v[28:31]
	v_mfma_f32_16x16x32_bf16 v[36:39], v[172:175], v[196:199], v[36:39]
	v_mfma_f32_16x16x32_bf16 v[36:39], v[168:171], v[192:195], v[36:39]
	v_mfma_f32_16x16x32_bf16 v[40:43], v[160:163], v[192:195], v[40:43]
	v_mfma_f32_16x16x32_bf16 v[40:43], v[164:167], v[196:199], v[40:43]
	v_mfma_f32_16x16x32_bf16 v[48:51], v[156:159], v[196:199], v[48:51]
	v_mfma_f32_16x16x32_bf16 v[48:51], v[146:149], v[192:195], v[48:51]
	v_mfma_f32_16x16x32_bf16 v[32:35], v[146:149], v[200:203], v[32:35]
	v_mfma_f32_16x16x32_bf16 v[32:35], v[156:159], v[204:207], v[32:35]
	v_mfma_f32_16x16x32_bf16 v[24:27], v[164:167], v[204:207], v[24:27]
	v_mfma_f32_16x16x32_bf16 v[24:27], v[160:163], v[200:203], v[24:27]
	v_mfma_f32_16x16x32_bf16 v[20:23], v[168:171], v[200:203], v[20:23]
	v_mfma_f32_16x16x32_bf16 v[20:23], v[172:175], v[204:207], v[20:23]
	v_mfma_f32_16x16x32_bf16 v[12:15], v[180:183], v[204:207], v[12:15]
	v_mfma_f32_16x16x32_bf16 v[12:15], v[176:179], v[200:203], v[12:15]
	v_mfma_f32_16x16x32_bf16 v[0:3], v[176:179], v[208:211], v[0:3]
	v_mfma_f32_16x16x32_bf16 v[0:3], v[180:183], v[212:215], v[0:3]
	v_mfma_f32_16x16x32_bf16 v[4:7], v[172:175], v[212:215], v[4:7]
	v_mfma_f32_16x16x32_bf16 v[4:7], v[168:171], v[208:211], v[4:7]
	v_mfma_f32_16x16x32_bf16 v[8:11], v[160:163], v[208:211], v[8:11]
	v_mfma_f32_16x16x32_bf16 v[8:11], v[164:167], v[212:215], v[8:11]
	s_barrier
	s_setprio 3
	v_mfma_f32_16x16x32_bf16 v[16:19], v[156:159], v[212:215], v[16:19]
	v_mfma_f32_16x16x32_bf16 v[16:19], v[146:149], v[208:211], v[16:19]
	s_setprio 0
	s_add_i32 s46, s46, 2
	s_add_u32 s6, s6, 0x100
	s_addc_u32 s15, s15, 0
	s_cmp_gt_u32 s46, 13
	s_mov_b64 s[20:21], s[22:23]
	s_cbranch_scc0 .LBB0_1263
	s_and_b64 vcc, exec, s[8:9]
	s_cbranch_vccz .LBB0_1266
	s_barrier

.LBB0_1340:
	v_add_u32_e32 v166, s51, v152
	v_add_u32_e32 v182, s52, v152
	ds_read_b128 v[154:157], v166
	ds_read_b128 v[158:161], v166 offset:1024
	ds_read_b128 v[162:165], v166 offset:2048
	ds_read_b128 v[166:169], v166 offset:3072
	ds_read_b128 v[170:173], v182
	ds_read_b128 v[174:177], v182 offset:1024
	ds_read_b128 v[178:181], v182 offset:2048
	ds_read_b128 v[182:185], v182 offset:3072
	s_add_u32 s30, s10, s28
	s_addc_u32 s31, s11, s29
	s_cmp_eq_u32 s58, 60
	s_cselect_b32 s35, s23, s31
	s_cselect_b32 s34, s54, s30
	s_cselect_b32 s31, s21, s57
	s_cselect_b32 s30, s55, s56
	v_lshl_add_u64 v[186:187], s[10:11], 0, v[146:147]
	s_add_i32 m0, s44, 0xc000
	s_nop 0
	global_load_lds_dwordx4 v[186:187], off
	v_lshl_add_u64 v[186:187], s[10:11], 0, v[144:145]
	s_add_i32 m0, s44, 0xe000
	s_nop 0
	global_load_lds_dwordx4 v[186:187], off
	ds_read_b128 v[186:189], v153
	ds_read_b128 v[190:193], v153 offset:1024
	ds_read_b128 v[194:197], v153 offset:2048
	ds_read_b128 v[198:201], v153 offset:3072
	ds_read_b128 v[202:205], v153 offset:4096
	ds_read_b128 v[206:209], v153 offset:5120
	ds_read_b128 v[210:213], v153 offset:6144
	ds_read_b128 v[214:217], v153 offset:7168
	s_waitcnt vmcnt(8)
	s_waitcnt lgkmcnt(0)
	s_barrier
	v_mfma_f32_16x16x32_bf16 v[124:127], v[154:157], v[186:189], v[124:127]
	v_mfma_f32_16x16x32_bf16 v[124:127], v[158:161], v[190:193], v[124:127]
	v_mfma_f32_16x16x32_bf16 v[120:123], v[166:169], v[190:193], v[120:123]
	v_mfma_f32_16x16x32_bf16 v[120:123], v[162:165], v[186:189], v[120:123]
	v_mfma_f32_16x16x32_bf16 v[116:119], v[170:173], v[186:189], v[116:119]
	v_mfma_f32_16x16x32_bf16 v[116:119], v[174:177], v[190:193], v[116:119]
	v_mfma_f32_16x16x32_bf16 v[112:115], v[182:185], v[190:193], v[112:115]
	v_mfma_f32_16x16x32_bf16 v[112:115], v[178:181], v[186:189], v[112:115]
	v_mfma_f32_16x16x32_bf16 v[96:99], v[178:181], v[194:197], v[96:99]
	v_mfma_f32_16x16x32_bf16 v[96:99], v[182:185], v[198:201], v[96:99]
	v_mfma_f32_16x16x32_bf16 v[100:103], v[174:177], v[198:201], v[100:103]
	v_mfma_f32_16x16x32_bf16 v[100:103], v[170:173], v[194:197], v[100:103]
	v_mfma_f32_16x16x32_bf16 v[104:107], v[162:165], v[194:197], v[104:107]
	v_mfma_f32_16x16x32_bf16 v[104:107], v[166:169], v[198:201], v[104:107]
	v_mfma_f32_16x16x32_bf16 v[108:111], v[158:161], v[198:201], v[108:111]
	v_mfma_f32_16x16x32_bf16 v[108:111], v[154:157], v[194:197], v[108:111]
	v_mfma_f32_16x16x32_bf16 v[92:95], v[154:157], v[202:205], v[92:95]
	v_mfma_f32_16x16x32_bf16 v[92:95], v[158:161], v[206:209], v[92:95]
	v_mfma_f32_16x16x32_bf16 v[88:91], v[166:169], v[206:209], v[88:91]
	v_mfma_f32_16x16x32_bf16 v[88:91], v[162:165], v[202:205], v[88:91]
	v_mfma_f32_16x16x32_bf16 v[84:87], v[170:173], v[202:205], v[84:87]
	v_mfma_f32_16x16x32_bf16 v[84:87], v[174:177], v[206:209], v[84:87]
	v_mfma_f32_16x16x32_bf16 v[80:83], v[182:185], v[206:209], v[80:83]
	v_mfma_f32_16x16x32_bf16 v[80:83], v[178:181], v[202:205], v[80:83]
	v_mfma_f32_16x16x32_bf16 v[64:67], v[178:181], v[210:213], v[64:67]
	v_mfma_f32_16x16x32_bf16 v[64:67], v[182:185], v[214:217], v[64:67]
	v_mfma_f32_16x16x32_bf16 v[68:71], v[174:177], v[214:217], v[68:71]
	v_mfma_f32_16x16x32_bf16 v[68:71], v[170:173], v[210:213], v[68:71]
	v_mfma_f32_16x16x32_bf16 v[72:75], v[162:165], v[210:213], v[72:75]
	v_mfma_f32_16x16x32_bf16 v[72:75], v[166:169], v[214:217], v[72:75]
	s_barrier
	s_setprio 3
	v_mfma_f32_16x16x32_bf16 v[76:79], v[158:161], v[214:217], v[76:79]
	v_mfma_f32_16x16x32_bf16 v[76:79], v[154:157], v[210:213], v[76:79]
	s_setprio 0
	s_add_i32 s59, s51, s43
	v_lshl_add_u64 v[218:219], s[30:31], 0, v[130:131]
	s_mov_b32 m0, s59
	v_lshl_add_u64 v[220:221], s[30:31], 0, v[134:135]
	global_load_lds_dwordx4 v[218:219], off
	s_add_i32 m0, s59, 0x2000
	s_add_u32 s60, s30, 0x100000
	s_addc_u32 s61, s31, 0
	s_add_i32 s59, s52, s43
	global_load_lds_dwordx4 v[220:221], off
	v_lshl_add_u64 v[186:187], s[60:61], 0, v[130:131]
	s_mov_b32 m0, s59
	v_lshl_add_u64 v[222:223], s[34:35], 0, v[128:129]
	global_load_lds_dwordx4 v[186:187], off
	v_lshl_add_u64 v[186:187], s[60:61], 0, v[134:135]
	s_add_i32 m0, s59, 0x2000
	v_lshl_add_u64 v[224:225], s[34:35], 0, v[132:133]
	global_load_lds_dwordx4 v[186:187], off
	s_mov_b32 m0, s44
	s_nop 0
	global_load_lds_dwordx4 v[222:223], off
	s_mov_b32 m0, s45
	s_nop 0
	global_load_lds_dwordx4 v[224:225], off
	ds_read_b128 v[186:189], v153 offset:16384
	ds_read_b128 v[190:193], v153 offset:17408
	ds_read_b128 v[194:197], v153 offset:18432
	ds_read_b128 v[198:201], v153 offset:19456
	ds_read_b128 v[202:205], v153 offset:20480
	ds_read_b128 v[206:209], v153 offset:21504
	ds_read_b128 v[210:213], v153 offset:22528
	ds_read_b128 v[214:217], v153 offset:23552
	s_waitcnt vmcnt(8)
	s_waitcnt lgkmcnt(0)
	s_barrier
	v_mfma_f32_16x16x32_bf16 v[60:63], v[154:157], v[186:189], v[60:63]
	v_mfma_f32_16x16x32_bf16 v[60:63], v[158:161], v[190:193], v[60:63]
	v_mfma_f32_16x16x32_bf16 v[56:59], v[166:169], v[190:193], v[56:59]
	v_mfma_f32_16x16x32_bf16 v[56:59], v[162:165], v[186:189], v[56:59]
	v_mfma_f32_16x16x32_bf16 v[52:55], v[170:173], v[186:189], v[52:55]
	v_mfma_f32_16x16x32_bf16 v[52:55], v[174:177], v[190:193], v[52:55]
	v_mfma_f32_16x16x32_bf16 v[48:51], v[182:185], v[190:193], v[48:51]
	v_mfma_f32_16x16x32_bf16 v[48:51], v[178:181], v[186:189], v[48:51]
	v_mfma_f32_16x16x32_bf16 v[32:35], v[178:181], v[194:197], v[32:35]
	v_mfma_f32_16x16x32_bf16 v[32:35], v[182:185], v[198:201], v[32:35]
	v_mfma_f32_16x16x32_bf16 v[36:39], v[174:177], v[198:201], v[36:39]
	v_mfma_f32_16x16x32_bf16 v[36:39], v[170:173], v[194:197], v[36:39]
	v_mfma_f32_16x16x32_bf16 v[40:43], v[162:165], v[194:197], v[40:43]
	v_mfma_f32_16x16x32_bf16 v[40:43], v[166:169], v[198:201], v[40:43]
	v_mfma_f32_16x16x32_bf16 v[44:47], v[158:161], v[198:201], v[44:47]
	v_mfma_f32_16x16x32_bf16 v[44:47], v[154:157], v[194:197], v[44:47]
	v_mfma_f32_16x16x32_bf16 v[28:31], v[154:157], v[202:205], v[28:31]
	v_mfma_f32_16x16x32_bf16 v[28:31], v[158:161], v[206:209], v[28:31]
	v_mfma_f32_16x16x32_bf16 v[24:27], v[166:169], v[206:209], v[24:27]
	v_mfma_f32_16x16x32_bf16 v[24:27], v[162:165], v[202:205], v[24:27]
	v_mfma_f32_16x16x32_bf16 v[20:23], v[170:173], v[202:205], v[20:23]
	v_mfma_f32_16x16x32_bf16 v[20:23], v[174:177], v[206:209], v[20:23]
	v_mfma_f32_16x16x32_bf16 v[16:19], v[182:185], v[206:209], v[16:19]
	v_mfma_f32_16x16x32_bf16 v[16:19], v[178:181], v[202:205], v[16:19]
	v_mfma_f32_16x16x32_bf16 v[0:3], v[178:181], v[210:213], v[0:3]
	v_mfma_f32_16x16x32_bf16 v[0:3], v[182:185], v[214:217], v[0:3]
	v_mfma_f32_16x16x32_bf16 v[4:7], v[174:177], v[214:217], v[4:7]
	v_mfma_f32_16x16x32_bf16 v[4:7], v[170:173], v[210:213], v[4:7]
	v_mfma_f32_16x16x32_bf16 v[8:11], v[162:165], v[210:213], v[8:11]
	v_mfma_f32_16x16x32_bf16 v[8:11], v[166:169], v[214:217], v[8:11]
	s_barrier
	s_setprio 3
	v_mfma_f32_16x16x32_bf16 v[12:15], v[158:161], v[214:217], v[12:15]
	v_mfma_f32_16x16x32_bf16 v[12:15], v[154:157], v[210:213], v[12:15]
	s_setprio 0
	s_add_i32 s59, 0, 0x18000
	s_add_i32 s60, 0, 0x1c000
	v_add_u32_e32 v166, s59, v152
	v_add_u32_e32 v182, s60, v152
	ds_read_b128 v[154:157], v166
	ds_read_b128 v[158:161], v166 offset:1024
	ds_read_b128 v[162:165], v166 offset:2048
	ds_read_b128 v[166:169], v166 offset:3072
	ds_read_b128 v[170:173], v182
	ds_read_b128 v[174:177], v182 offset:1024
	ds_read_b128 v[178:181], v182 offset:2048
	ds_read_b128 v[182:185], v182 offset:3072
	s_add_u32 s34, s34, 0x100000
	s_addc_u32 s35, s35, 0
	s_mov_b32 m0, s46
	v_lshl_add_u64 v[186:187], s[34:35], 0, v[128:129]
	global_load_lds_dwordx4 v[186:187], off
	v_lshl_add_u64 v[186:187], s[34:35], 0, v[132:133]
	s_mov_b32 m0, s47
	s_nop 0
	global_load_lds_dwordx4 v[186:187], off
	ds_read_b128 v[186:189], v153 offset:32768
	ds_read_b128 v[190:193], v153 offset:33792
	ds_read_b128 v[194:197], v153 offset:34816
	ds_read_b128 v[198:201], v153 offset:35840
	ds_read_b128 v[202:205], v153 offset:36864
	ds_read_b128 v[206:209], v153 offset:37888
	ds_read_b128 v[210:213], v153 offset:38912
	ds_read_b128 v[214:217], v153 offset:39936
	s_waitcnt vmcnt(8)
	s_waitcnt lgkmcnt(0)
	s_barrier
	v_mfma_f32_16x16x32_bf16 v[124:127], v[154:157], v[186:189], v[124:127]
	v_mfma_f32_16x16x32_bf16 v[124:127], v[158:161], v[190:193], v[124:127]
	v_mfma_f32_16x16x32_bf16 v[120:123], v[166:169], v[190:193], v[120:123]
	v_mfma_f32_16x16x32_bf16 v[120:123], v[162:165], v[186:189], v[120:123]
	v_mfma_f32_16x16x32_bf16 v[116:119], v[170:173], v[186:189], v[116:119]
	v_mfma_f32_16x16x32_bf16 v[116:119], v[174:177], v[190:193], v[116:119]
	v_mfma_f32_16x16x32_bf16 v[112:115], v[182:185], v[190:193], v[112:115]
	v_mfma_f32_16x16x32_bf16 v[112:115], v[178:181], v[186:189], v[112:115]
	v_mfma_f32_16x16x32_bf16 v[96:99], v[178:181], v[194:197], v[96:99]
	v_mfma_f32_16x16x32_bf16 v[96:99], v[182:185], v[198:201], v[96:99]
	v_mfma_f32_16x16x32_bf16 v[100:103], v[174:177], v[198:201], v[100:103]
	v_mfma_f32_16x16x32_bf16 v[100:103], v[170:173], v[194:197], v[100:103]
	v_mfma_f32_16x16x32_bf16 v[104:107], v[162:165], v[194:197], v[104:107]
	v_mfma_f32_16x16x32_bf16 v[104:107], v[166:169], v[198:201], v[104:107]
	v_mfma_f32_16x16x32_bf16 v[108:111], v[158:161], v[198:201], v[108:111]
	v_mfma_f32_16x16x32_bf16 v[108:111], v[154:157], v[194:197], v[108:111]
	v_mfma_f32_16x16x32_bf16 v[92:95], v[154:157], v[202:205], v[92:95]
	v_mfma_f32_16x16x32_bf16 v[92:95], v[158:161], v[206:209], v[92:95]
	v_mfma_f32_16x16x32_bf16 v[88:91], v[166:169], v[206:209], v[88:91]
	v_mfma_f32_16x16x32_bf16 v[88:91], v[162:165], v[202:205], v[88:91]
	v_mfma_f32_16x16x32_bf16 v[84:87], v[170:173], v[202:205], v[84:87]
	v_mfma_f32_16x16x32_bf16 v[84:87], v[174:177], v[206:209], v[84:87]
	v_mfma_f32_16x16x32_bf16 v[80:83], v[182:185], v[206:209], v[80:83]
	v_mfma_f32_16x16x32_bf16 v[80:83], v[178:181], v[202:205], v[80:83]
	v_mfma_f32_16x16x32_bf16 v[64:67], v[178:181], v[210:213], v[64:67]
	v_mfma_f32_16x16x32_bf16 v[64:67], v[182:185], v[214:217], v[64:67]
	v_mfma_f32_16x16x32_bf16 v[68:71], v[174:177], v[214:217], v[68:71]
	v_mfma_f32_16x16x32_bf16 v[68:71], v[170:173], v[210:213], v[68:71]
	v_mfma_f32_16x16x32_bf16 v[72:75], v[162:165], v[210:213], v[72:75]
	v_mfma_f32_16x16x32_bf16 v[72:75], v[166:169], v[214:217], v[72:75]
	s_barrier
	s_setprio 3
	v_mfma_f32_16x16x32_bf16 v[76:79], v[158:161], v[214:217], v[76:79]
	v_mfma_f32_16x16x32_bf16 v[76:79], v[154:157], v[210:213], v[76:79]
	s_setprio 0
	s_add_i32 s34, s59, s43
	v_lshl_add_u64 v[186:187], v[218:219], 0, s[14:15]
	s_mov_b32 m0, s34
	s_nop 0
	global_load_lds_dwordx4 v[186:187], off
	s_add_i32 m0, s34, 0x2000
	s_add_u32 s30, s30, 0x100080
	v_lshl_add_u64 v[186:187], v[220:221], 0, s[14:15]
	s_addc_u32 s31, s31, 0
	s_add_i32 s34, s60, s43
	global_load_lds_dwordx4 v[186:187], off
	v_lshl_add_u64 v[186:187], s[30:31], 0, v[130:131]
	s_mov_b32 m0, s34
	s_nop 0
	global_load_lds_dwordx4 v[186:187], off
	v_lshl_add_u64 v[186:187], s[30:31], 0, v[134:135]
	s_add_i32 m0, s34, 0x2000
	s_nop 0
	global_load_lds_dwordx4 v[186:187], off
	v_lshl_add_u64 v[186:187], v[222:223], 0, s[16:17]
	s_mov_b32 m0, s49
	s_nop 0
	global_load_lds_dwordx4 v[186:187], off
	v_lshl_add_u64 v[186:187], v[224:225], 0, s[16:17]
	s_mov_b32 m0, s50
	s_nop 0
	global_load_lds_dwordx4 v[186:187], off
	ds_read_b128 v[186:189], v153 offset:49152
	ds_read_b128 v[190:193], v153 offset:50176
	ds_read_b128 v[194:197], v153 offset:51200
	ds_read_b128 v[198:201], v153 offset:52224
	ds_read_b128 v[202:205], v153 offset:53248
	ds_read_b128 v[206:209], v153 offset:54272
	ds_read_b128 v[210:213], v153 offset:55296
	ds_read_b128 v[214:217], v153 offset:56320
	s_waitcnt vmcnt(8)
	s_waitcnt lgkmcnt(0)
	s_barrier
	v_mfma_f32_16x16x32_bf16 v[60:63], v[154:157], v[186:189], v[60:63]
	v_mfma_f32_16x16x32_bf16 v[60:63], v[158:161], v[190:193], v[60:63]
	v_mfma_f32_16x16x32_bf16 v[56:59], v[166:169], v[190:193], v[56:59]
	v_mfma_f32_16x16x32_bf16 v[56:59], v[162:165], v[186:189], v[56:59]
	v_mfma_f32_16x16x32_bf16 v[52:55], v[170:173], v[186:189], v[52:55]
	v_mfma_f32_16x16x32_bf16 v[52:55], v[174:177], v[190:193], v[52:55]
	v_mfma_f32_16x16x32_bf16 v[48:51], v[182:185], v[190:193], v[48:51]
	v_mfma_f32_16x16x32_bf16 v[48:51], v[178:181], v[186:189], v[48:51]
	v_mfma_f32_16x16x32_bf16 v[32:35], v[178:181], v[194:197], v[32:35]
	v_mfma_f32_16x16x32_bf16 v[32:35], v[182:185], v[198:201], v[32:35]
	v_mfma_f32_16x16x32_bf16 v[36:39], v[174:177], v[198:201], v[36:39]
	v_mfma_f32_16x16x32_bf16 v[36:39], v[170:173], v[194:197], v[36:39]
	v_mfma_f32_16x16x32_bf16 v[40:43], v[162:165], v[194:197], v[40:43]
	v_mfma_f32_16x16x32_bf16 v[40:43], v[166:169], v[198:201], v[40:43]
	v_mfma_f32_16x16x32_bf16 v[44:47], v[158:161], v[198:201], v[44:47]
	v_mfma_f32_16x16x32_bf16 v[44:47], v[154:157], v[194:197], v[44:47]
	v_mfma_f32_16x16x32_bf16 v[28:31], v[154:157], v[202:205], v[28:31]
	v_mfma_f32_16x16x32_bf16 v[28:31], v[158:161], v[206:209], v[28:31]
	v_mfma_f32_16x16x32_bf16 v[24:27], v[166:169], v[206:209], v[24:27]
	v_mfma_f32_16x16x32_bf16 v[24:27], v[162:165], v[202:205], v[24:27]
	v_mfma_f32_16x16x32_bf16 v[20:23], v[170:173], v[202:205], v[20:23]
	v_mfma_f32_16x16x32_bf16 v[20:23], v[174:177], v[206:209], v[20:23]
	v_mfma_f32_16x16x32_bf16 v[16:19], v[182:185], v[206:209], v[16:19]
	v_mfma_f32_16x16x32_bf16 v[16:19], v[178:181], v[202:205], v[16:19]
	v_mfma_f32_16x16x32_bf16 v[0:3], v[178:181], v[210:213], v[0:3]
	v_mfma_f32_16x16x32_bf16 v[0:3], v[182:185], v[214:217], v[0:3]
	v_mfma_f32_16x16x32_bf16 v[4:7], v[174:177], v[214:217], v[4:7]
	v_mfma_f32_16x16x32_bf16 v[4:7], v[170:173], v[210:213], v[4:7]
	v_mfma_f32_16x16x32_bf16 v[8:11], v[162:165], v[210:213], v[8:11]
	v_mfma_f32_16x16x32_bf16 v[8:11], v[166:169], v[214:217], v[8:11]
	s_barrier
	s_setprio 3
	v_mfma_f32_16x16x32_bf16 v[12:15], v[158:161], v[214:217], v[12:15]
	v_mfma_f32_16x16x32_bf16 v[12:15], v[154:157], v[210:213], v[12:15]
	s_setprio 0
	s_add_i32 s58, s58, 2
	s_add_u32 s56, s56, 0x100
	s_addc_u32 s57, s57, 0
	s_add_u32 s28, s28, 0x1000
	s_addc_u32 s29, s29, 0
	v_lshl_add_u64 v[146:147], v[146:147], 0, s[18:19]
	s_cmp_gt_u32 s58, 61
	v_lshl_add_u64 v[144:145], v[144:145], 0, s[18:19]
	s_cbranch_scc0 .LBB0_1340
	s_andn2_b64 vcc, exec, s[4:5]
	s_cbranch_vccnz .LBB0_1332
	v_mov_b32_e32 v0, 0
	s_mov_b32 s7, s20
	s_mov_b32 s6, s22
	s_mov_b64 s[8:9], s[26:27]
	s_mov_b64 s[10:11], s[24:25]
	s_mov_b32 s48, s53
	v_mov_b32_e32 v1, v0
	v_mov_b32_e32 v2, v0
	v_mov_b32_e32 v3, v0
	v_mov_b32_e32 v4, v0
	v_mov_b32_e32 v5, v0
	v_mov_b32_e32 v6, v0
	v_mov_b32_e32 v7, v0
	v_mov_b32_e32 v16, v0
	v_mov_b32_e32 v17, v0
	v_mov_b32_e32 v18, v0
	v_mov_b32_e32 v19, v0
	v_mov_b32_e32 v20, v0
	v_mov_b32_e32 v21, v0
	v_mov_b32_e32 v22, v0
	v_mov_b32_e32 v23, v0
	v_mov_b32_e32 v32, v0
	v_mov_b32_e32 v33, v0
	v_mov_b32_e32 v34, v0
	v_mov_b32_e32 v35, v0
	v_mov_b32_e32 v36, v0
	v_mov_b32_e32 v37, v0
	v_mov_b32_e32 v38, v0
	v_mov_b32_e32 v39, v0
	v_mov_b32_e32 v48, v0
	v_mov_b32_e32 v49, v0
	v_mov_b32_e32 v50, v0
	v_mov_b32_e32 v51, v0
	v_mov_b32_e32 v52, v0
	v_mov_b32_e32 v53, v0
	v_mov_b32_e32 v54, v0
	v_mov_b32_e32 v55, v0
	v_mov_b32_e32 v8, v0
	v_mov_b32_e32 v9, v0
	v_mov_b32_e32 v10, v0
	v_mov_b32_e32 v11, v0
	v_mov_b32_e32 v12, v0
	v_mov_b32_e32 v13, v0
	v_mov_b32_e32 v14, v0
	v_mov_b32_e32 v15, v0
	v_mov_b32_e32 v24, v0
	v_mov_b32_e32 v25, v0
	v_mov_b32_e32 v26, v0
	v_mov_b32_e32 v27, v0
	v_mov_b32_e32 v28, v0
	v_mov_b32_e32 v29, v0
	v_mov_b32_e32 v30, v0
	v_mov_b32_e32 v31, v0
	v_mov_b32_e32 v40, v0
	v_mov_b32_e32 v41, v0
	v_mov_b32_e32 v42, v0
	v_mov_b32_e32 v43, v0
	v_mov_b32_e32 v44, v0
	v_mov_b32_e32 v45, v0
	v_mov_b32_e32 v46, v0
	v_mov_b32_e32 v47, v0
	v_mov_b32_e32 v56, v0
	v_mov_b32_e32 v57, v0
	v_mov_b32_e32 v58, v0
	v_mov_b32_e32 v59, v0
	v_mov_b32_e32 v60, v0
	v_mov_b32_e32 v61, v0
	v_mov_b32_e32 v62, v0
	v_mov_b32_e32 v63, v0
	v_mov_b32_e32 v64, v0
	v_mov_b32_e32 v65, v0
	v_mov_b32_e32 v66, v0
	v_mov_b32_e32 v67, v0
	v_mov_b32_e32 v68, v0
	v_mov_b32_e32 v69, v0
	v_mov_b32_e32 v70, v0
	v_mov_b32_e32 v71, v0
	v_mov_b32_e32 v80, v0
	v_mov_b32_e32 v81, v0
	v_mov_b32_e32 v82, v0
	v_mov_b32_e32 v83, v0
	v_mov_b32_e32 v84, v0
	v_mov_b32_e32 v85, v0
	v_mov_b32_e32 v86, v0
	v_mov_b32_e32 v87, v0
	v_mov_b32_e32 v96, v0
	v_mov_b32_e32 v97, v0
	v_mov_b32_e32 v98, v0
	v_mov_b32_e32 v99, v0
	v_mov_b32_e32 v100, v0
	v_mov_b32_e32 v101, v0
	v_mov_b32_e32 v102, v0
	v_mov_b32_e32 v103, v0
	v_mov_b32_e32 v112, v0
	v_mov_b32_e32 v113, v0
	v_mov_b32_e32 v114, v0
	v_mov_b32_e32 v115, v0
	v_mov_b32_e32 v116, v0
	v_mov_b32_e32 v117, v0
	v_mov_b32_e32 v118, v0
	v_mov_b32_e32 v119, v0
	v_mov_b32_e32 v72, v0
	v_mov_b32_e32 v73, v0
	v_mov_b32_e32 v74, v0
	v_mov_b32_e32 v75, v0
	v_mov_b32_e32 v76, v0
	v_mov_b32_e32 v77, v0
	v_mov_b32_e32 v78, v0
	v_mov_b32_e32 v79, v0
	v_mov_b32_e32 v88, v0
	v_mov_b32_e32 v89, v0
	v_mov_b32_e32 v90, v0
	v_mov_b32_e32 v91, v0
	v_mov_b32_e32 v92, v0
	v_mov_b32_e32 v93, v0
	v_mov_b32_e32 v94, v0
	v_mov_b32_e32 v95, v0
	v_mov_b32_e32 v104, v0
	v_mov_b32_e32 v105, v0
	v_mov_b32_e32 v106, v0
	v_mov_b32_e32 v107, v0
	v_mov_b32_e32 v108, v0
	v_mov_b32_e32 v109, v0
	v_mov_b32_e32 v110, v0
	v_mov_b32_e32 v111, v0
	v_mov_b32_e32 v120, v0
	v_mov_b32_e32 v121, v0
	v_mov_b32_e32 v122, v0
	v_mov_b32_e32 v123, v0
	v_mov_b32_e32 v124, v0
	v_mov_b32_e32 v125, v0
	v_mov_b32_e32 v126, v0
	v_mov_b32_e32 v127, v0
	s_branch .LBB0_1332

.LBB0_1435:
	ds_read_b128 v[128:131], v180
	ds_read_b128 v[132:135], v180 offset:1024
	ds_read_b128 v[136:139], v180 offset:2048
	ds_read_b128 v[140:143], v180 offset:3072
	ds_read_b128 v[144:147], v181
	ds_read_b128 v[148:151], v181 offset:1024
	ds_read_b128 v[170:173], v181 offset:2048
	ds_read_b128 v[174:177], v181 offset:3072
	s_add_u32 s26, s24, 0xfffc0080
	s_addc_u32 s27, s25, -1
	s_cmp_eq_u32 s35, 12
	s_cselect_b32 s29, s1, s27
	s_cselect_b32 s28, s19, s26
	s_cselect_b32 s27, s17, s34
	s_cselect_b32 s26, s30, s31
	v_lshl_add_u64 v[184:185], s[24:25], 0, v[162:163]
	s_add_i32 m0, s40, 0xc000
	s_nop 0
	global_load_lds_dwordx4 v[184:185], off
	v_lshl_add_u64 v[184:185], s[24:25], 0, v[164:165]
	s_add_i32 m0, s40, 0xe000
	s_nop 0
	global_load_lds_dwordx4 v[184:185], off
	ds_read_b128 v[184:187], v182
	ds_read_b128 v[188:191], v182 offset:1024
	ds_read_b128 v[192:195], v182 offset:2048
	ds_read_b128 v[196:199], v182 offset:3072
	ds_read_b128 v[200:203], v182 offset:4096
	ds_read_b128 v[204:207], v182 offset:5120
	ds_read_b128 v[208:211], v182 offset:6144
	ds_read_b128 v[212:215], v182 offset:7168
	s_waitcnt vmcnt(8)
	s_waitcnt lgkmcnt(0)
	s_barrier
	v_mfma_f32_16x16x32_bf16 v[124:127], v[128:131], v[184:187], v[124:127]
	v_mfma_f32_16x16x32_bf16 v[124:127], v[132:135], v[188:191], v[124:127]
	v_mfma_f32_16x16x32_bf16 v[120:123], v[140:143], v[188:191], v[120:123]
	v_mfma_f32_16x16x32_bf16 v[120:123], v[136:139], v[184:187], v[120:123]
	v_mfma_f32_16x16x32_bf16 v[116:119], v[144:147], v[184:187], v[116:119]
	v_mfma_f32_16x16x32_bf16 v[116:119], v[148:151], v[188:191], v[116:119]
	v_mfma_f32_16x16x32_bf16 v[112:115], v[174:177], v[188:191], v[112:115]
	v_mfma_f32_16x16x32_bf16 v[112:115], v[170:173], v[184:187], v[112:115]
	v_mfma_f32_16x16x32_bf16 v[96:99], v[170:173], v[192:195], v[96:99]
	v_mfma_f32_16x16x32_bf16 v[96:99], v[174:177], v[196:199], v[96:99]
	v_mfma_f32_16x16x32_bf16 v[100:103], v[148:151], v[196:199], v[100:103]
	v_mfma_f32_16x16x32_bf16 v[100:103], v[144:147], v[192:195], v[100:103]
	v_mfma_f32_16x16x32_bf16 v[104:107], v[136:139], v[192:195], v[104:107]
	v_mfma_f32_16x16x32_bf16 v[104:107], v[140:143], v[196:199], v[104:107]
	v_mfma_f32_16x16x32_bf16 v[108:111], v[132:135], v[196:199], v[108:111]
	v_mfma_f32_16x16x32_bf16 v[108:111], v[128:131], v[192:195], v[108:111]
	v_mfma_f32_16x16x32_bf16 v[92:95], v[128:131], v[200:203], v[92:95]
	v_mfma_f32_16x16x32_bf16 v[92:95], v[132:135], v[204:207], v[92:95]
	v_mfma_f32_16x16x32_bf16 v[88:91], v[140:143], v[204:207], v[88:91]
	v_mfma_f32_16x16x32_bf16 v[88:91], v[136:139], v[200:203], v[88:91]
	v_mfma_f32_16x16x32_bf16 v[84:87], v[144:147], v[200:203], v[84:87]
	v_mfma_f32_16x16x32_bf16 v[84:87], v[148:151], v[204:207], v[84:87]
	v_mfma_f32_16x16x32_bf16 v[80:83], v[174:177], v[204:207], v[80:83]
	v_mfma_f32_16x16x32_bf16 v[80:83], v[170:173], v[200:203], v[80:83]
	v_mfma_f32_16x16x32_bf16 v[64:67], v[170:173], v[208:211], v[64:67]
	v_mfma_f32_16x16x32_bf16 v[64:67], v[174:177], v[212:215], v[64:67]
	v_mfma_f32_16x16x32_bf16 v[68:71], v[148:151], v[212:215], v[68:71]
	v_mfma_f32_16x16x32_bf16 v[68:71], v[144:147], v[208:211], v[68:71]
	v_mfma_f32_16x16x32_bf16 v[72:75], v[136:139], v[208:211], v[72:75]
	v_mfma_f32_16x16x32_bf16 v[72:75], v[140:143], v[212:215], v[72:75]
	s_barrier
	s_setprio 3
	v_mfma_f32_16x16x32_bf16 v[76:79], v[132:135], v[212:215], v[76:79]
	v_mfma_f32_16x16x32_bf16 v[76:79], v[128:131], v[208:211], v[76:79]
	s_setprio 0
	s_add_i32 s54, s50, s39
	v_lshl_add_u64 v[216:217], s[26:27], 0, v[154:155]
	s_mov_b32 m0, s54
	v_lshl_add_u64 v[218:219], s[26:27], 0, v[158:159]
	global_load_lds_dwordx4 v[216:217], off
	s_add_i32 m0, s54, 0x2000
	s_add_u32 s54, s26, 0x100000
	s_addc_u32 s55, s27, 0
	s_add_i32 s56, s51, s39
	global_load_lds_dwordx4 v[218:219], off
	v_lshl_add_u64 v[184:185], s[54:55], 0, v[154:155]
	s_mov_b32 m0, s56
	v_lshl_add_u64 v[220:221], s[28:29], 0, v[152:153]
	global_load_lds_dwordx4 v[184:185], off
	v_lshl_add_u64 v[184:185], s[54:55], 0, v[158:159]
	s_add_i32 m0, s56, 0x2000
	v_lshl_add_u64 v[222:223], s[28:29], 0, v[156:157]
	global_load_lds_dwordx4 v[184:185], off
	s_mov_b32 m0, s40
	s_nop 0
	global_load_lds_dwordx4 v[220:221], off
	s_mov_b32 m0, s41
	s_nop 0
	global_load_lds_dwordx4 v[222:223], off
	ds_read_b128 v[184:187], v182 offset:16384
	ds_read_b128 v[188:191], v182 offset:17408
	ds_read_b128 v[192:195], v182 offset:18432
	ds_read_b128 v[196:199], v182 offset:19456
	ds_read_b128 v[200:203], v182 offset:20480
	ds_read_b128 v[204:207], v182 offset:21504
	ds_read_b128 v[208:211], v182 offset:22528
	ds_read_b128 v[212:215], v182 offset:23552
	s_waitcnt vmcnt(8)
	s_waitcnt lgkmcnt(0)
	s_barrier
	v_mfma_f32_16x16x32_bf16 v[60:63], v[128:131], v[184:187], v[60:63]
	v_mfma_f32_16x16x32_bf16 v[60:63], v[132:135], v[188:191], v[60:63]
	v_mfma_f32_16x16x32_bf16 v[56:59], v[140:143], v[188:191], v[56:59]
	v_mfma_f32_16x16x32_bf16 v[56:59], v[136:139], v[184:187], v[56:59]
	v_mfma_f32_16x16x32_bf16 v[52:55], v[144:147], v[184:187], v[52:55]
	v_mfma_f32_16x16x32_bf16 v[52:55], v[148:151], v[188:191], v[52:55]
	v_mfma_f32_16x16x32_bf16 v[48:51], v[174:177], v[188:191], v[48:51]
	v_mfma_f32_16x16x32_bf16 v[48:51], v[170:173], v[184:187], v[48:51]
	v_mfma_f32_16x16x32_bf16 v[32:35], v[170:173], v[192:195], v[32:35]
	v_mfma_f32_16x16x32_bf16 v[32:35], v[174:177], v[196:199], v[32:35]
	v_mfma_f32_16x16x32_bf16 v[36:39], v[148:151], v[196:199], v[36:39]
	v_mfma_f32_16x16x32_bf16 v[36:39], v[144:147], v[192:195], v[36:39]
	v_mfma_f32_16x16x32_bf16 v[40:43], v[136:139], v[192:195], v[40:43]
	v_mfma_f32_16x16x32_bf16 v[40:43], v[140:143], v[196:199], v[40:43]
	v_mfma_f32_16x16x32_bf16 v[44:47], v[132:135], v[196:199], v[44:47]
	v_mfma_f32_16x16x32_bf16 v[44:47], v[128:131], v[192:195], v[44:47]
	v_mfma_f32_16x16x32_bf16 v[28:31], v[128:131], v[200:203], v[28:31]
	v_mfma_f32_16x16x32_bf16 v[28:31], v[132:135], v[204:207], v[28:31]
	v_mfma_f32_16x16x32_bf16 v[24:27], v[140:143], v[204:207], v[24:27]
	v_mfma_f32_16x16x32_bf16 v[24:27], v[136:139], v[200:203], v[24:27]
	v_mfma_f32_16x16x32_bf16 v[20:23], v[144:147], v[200:203], v[20:23]
	v_mfma_f32_16x16x32_bf16 v[20:23], v[148:151], v[204:207], v[20:23]
	v_mfma_f32_16x16x32_bf16 v[16:19], v[174:177], v[204:207], v[16:19]
	v_mfma_f32_16x16x32_bf16 v[16:19], v[170:173], v[200:203], v[16:19]
	v_mfma_f32_16x16x32_bf16 v[0:3], v[170:173], v[208:211], v[0:3]
	v_mfma_f32_16x16x32_bf16 v[0:3], v[174:177], v[212:215], v[0:3]
	v_mfma_f32_16x16x32_bf16 v[4:7], v[148:151], v[212:215], v[4:7]
	v_mfma_f32_16x16x32_bf16 v[4:7], v[144:147], v[208:211], v[4:7]
	v_mfma_f32_16x16x32_bf16 v[8:11], v[136:139], v[208:211], v[8:11]
	v_mfma_f32_16x16x32_bf16 v[8:11], v[140:143], v[212:215], v[8:11]
	s_barrier
	s_setprio 3
	v_mfma_f32_16x16x32_bf16 v[12:15], v[132:135], v[212:215], v[12:15]
	v_mfma_f32_16x16x32_bf16 v[12:15], v[128:131], v[208:211], v[12:15]
	s_setprio 0
	s_add_i32 s54, 0, 0x18000
	s_add_i32 s55, 0, 0x1c000
	v_add_u32_e32 v140, s54, v178
	v_add_u32_e32 v174, s55, v178
	ds_read_b128 v[128:131], v140
	ds_read_b128 v[132:135], v140 offset:1024
	ds_read_b128 v[136:139], v140 offset:2048
	ds_read_b128 v[140:143], v140 offset:3072
	ds_read_b128 v[144:147], v174
	ds_read_b128 v[148:151], v174 offset:1024
	ds_read_b128 v[170:173], v174 offset:2048
	ds_read_b128 v[174:177], v174 offset:3072
	s_add_u32 s28, s28, 0x40000
	s_addc_u32 s29, s29, 0
	s_mov_b32 m0, s42
	v_lshl_add_u64 v[184:185], s[28:29], 0, v[152:153]
	global_load_lds_dwordx4 v[184:185], off
	v_lshl_add_u64 v[184:185], s[28:29], 0, v[156:157]
	s_mov_b32 m0, s43
	s_nop 0
	global_load_lds_dwordx4 v[184:185], off
	ds_read_b128 v[184:187], v182 offset:32768
	ds_read_b128 v[188:191], v182 offset:33792
	ds_read_b128 v[192:195], v182 offset:34816
	ds_read_b128 v[196:199], v182 offset:35840
	ds_read_b128 v[200:203], v182 offset:36864
	ds_read_b128 v[204:207], v182 offset:37888
	ds_read_b128 v[208:211], v182 offset:38912
	ds_read_b128 v[212:215], v182 offset:39936
	s_waitcnt vmcnt(8)
	s_waitcnt lgkmcnt(0)
	s_barrier
	v_mfma_f32_16x16x32_bf16 v[124:127], v[128:131], v[184:187], v[124:127]
	v_mfma_f32_16x16x32_bf16 v[124:127], v[132:135], v[188:191], v[124:127]
	v_mfma_f32_16x16x32_bf16 v[120:123], v[140:143], v[188:191], v[120:123]
	v_mfma_f32_16x16x32_bf16 v[120:123], v[136:139], v[184:187], v[120:123]
	v_mfma_f32_16x16x32_bf16 v[116:119], v[144:147], v[184:187], v[116:119]
	v_mfma_f32_16x16x32_bf16 v[116:119], v[148:151], v[188:191], v[116:119]
	v_mfma_f32_16x16x32_bf16 v[112:115], v[174:177], v[188:191], v[112:115]
	v_mfma_f32_16x16x32_bf16 v[112:115], v[170:173], v[184:187], v[112:115]
	v_mfma_f32_16x16x32_bf16 v[96:99], v[170:173], v[192:195], v[96:99]
	v_mfma_f32_16x16x32_bf16 v[96:99], v[174:177], v[196:199], v[96:99]
	v_mfma_f32_16x16x32_bf16 v[100:103], v[148:151], v[196:199], v[100:103]
	v_mfma_f32_16x16x32_bf16 v[100:103], v[144:147], v[192:195], v[100:103]
	v_mfma_f32_16x16x32_bf16 v[104:107], v[136:139], v[192:195], v[104:107]
	v_mfma_f32_16x16x32_bf16 v[104:107], v[140:143], v[196:199], v[104:107]
	v_mfma_f32_16x16x32_bf16 v[108:111], v[132:135], v[196:199], v[108:111]
	v_mfma_f32_16x16x32_bf16 v[108:111], v[128:131], v[192:195], v[108:111]
	v_mfma_f32_16x16x32_bf16 v[92:95], v[128:131], v[200:203], v[92:95]
	v_mfma_f32_16x16x32_bf16 v[92:95], v[132:135], v[204:207], v[92:95]
	v_mfma_f32_16x16x32_bf16 v[88:91], v[140:143], v[204:207], v[88:91]
	v_mfma_f32_16x16x32_bf16 v[88:91], v[136:139], v[200:203], v[88:91]
	v_mfma_f32_16x16x32_bf16 v[84:87], v[144:147], v[200:203], v[84:87]
	v_mfma_f32_16x16x32_bf16 v[84:87], v[148:151], v[204:207], v[84:87]
	v_mfma_f32_16x16x32_bf16 v[80:83], v[174:177], v[204:207], v[80:83]
	v_mfma_f32_16x16x32_bf16 v[80:83], v[170:173], v[200:203], v[80:83]
	v_mfma_f32_16x16x32_bf16 v[64:67], v[170:173], v[208:211], v[64:67]
	v_mfma_f32_16x16x32_bf16 v[64:67], v[174:177], v[212:215], v[64:67]
	v_mfma_f32_16x16x32_bf16 v[68:71], v[148:151], v[212:215], v[68:71]
	v_mfma_f32_16x16x32_bf16 v[68:71], v[144:147], v[208:211], v[68:71]
	v_mfma_f32_16x16x32_bf16 v[72:75], v[136:139], v[208:211], v[72:75]
	v_mfma_f32_16x16x32_bf16 v[72:75], v[140:143], v[212:215], v[72:75]
	s_barrier
	s_setprio 3
	v_mfma_f32_16x16x32_bf16 v[76:79], v[132:135], v[212:215], v[76:79]
	v_mfma_f32_16x16x32_bf16 v[76:79], v[128:131], v[208:211], v[76:79]
	s_setprio 0
	s_add_i32 s28, s54, s39
	v_lshl_add_u64 v[184:185], v[216:217], 0, s[14:15]
	s_mov_b32 m0, s28
	s_nop 0
	global_load_lds_dwordx4 v[184:185], off
	s_add_i32 m0, s28, 0x2000
	s_add_u32 s26, s26, 0x100080
	v_lshl_add_u64 v[184:185], v[218:219], 0, s[14:15]
	s_addc_u32 s27, s27, 0
	s_add_i32 s28, s55, s39
	global_load_lds_dwordx4 v[184:185], off
	v_lshl_add_u64 v[184:185], s[26:27], 0, v[154:155]
	s_mov_b32 m0, s28
	s_nop 0
	global_load_lds_dwordx4 v[184:185], off
	v_lshl_add_u64 v[184:185], s[26:27], 0, v[158:159]
	s_add_i32 m0, s28, 0x2000
	s_nop 0
	global_load_lds_dwordx4 v[184:185], off
	v_lshl_add_u64 v[184:185], v[220:221], 0, s[14:15]
	s_mov_b32 m0, s45
	s_nop 0
	global_load_lds_dwordx4 v[184:185], off
	v_lshl_add_u64 v[184:185], v[222:223], 0, s[14:15]
	s_mov_b32 m0, s46
	s_nop 0
	global_load_lds_dwordx4 v[184:185], off
	ds_read_b128 v[184:187], v182 offset:49152
	ds_read_b128 v[188:191], v182 offset:50176
	ds_read_b128 v[192:195], v182 offset:51200
	ds_read_b128 v[196:199], v182 offset:52224
	ds_read_b128 v[200:203], v182 offset:53248
	ds_read_b128 v[204:207], v182 offset:54272
	ds_read_b128 v[208:211], v182 offset:55296
	ds_read_b128 v[212:215], v182 offset:56320
	s_waitcnt vmcnt(8)
	s_waitcnt lgkmcnt(0)
	s_barrier
	v_mfma_f32_16x16x32_bf16 v[60:63], v[128:131], v[184:187], v[60:63]
	v_mfma_f32_16x16x32_bf16 v[60:63], v[132:135], v[188:191], v[60:63]
	v_mfma_f32_16x16x32_bf16 v[56:59], v[140:143], v[188:191], v[56:59]
	v_mfma_f32_16x16x32_bf16 v[56:59], v[136:139], v[184:187], v[56:59]
	v_mfma_f32_16x16x32_bf16 v[52:55], v[144:147], v[184:187], v[52:55]
	v_mfma_f32_16x16x32_bf16 v[52:55], v[148:151], v[188:191], v[52:55]
	v_mfma_f32_16x16x32_bf16 v[48:51], v[174:177], v[188:191], v[48:51]
	v_mfma_f32_16x16x32_bf16 v[48:51], v[170:173], v[184:187], v[48:51]
	v_mfma_f32_16x16x32_bf16 v[32:35], v[170:173], v[192:195], v[32:35]
	v_mfma_f32_16x16x32_bf16 v[32:35], v[174:177], v[196:199], v[32:35]
	v_mfma_f32_16x16x32_bf16 v[36:39], v[148:151], v[196:199], v[36:39]
	v_mfma_f32_16x16x32_bf16 v[36:39], v[144:147], v[192:195], v[36:39]
	v_mfma_f32_16x16x32_bf16 v[40:43], v[136:139], v[192:195], v[40:43]
	v_mfma_f32_16x16x32_bf16 v[40:43], v[140:143], v[196:199], v[40:43]
	v_mfma_f32_16x16x32_bf16 v[44:47], v[132:135], v[196:199], v[44:47]
	v_mfma_f32_16x16x32_bf16 v[44:47], v[128:131], v[192:195], v[44:47]
	v_mfma_f32_16x16x32_bf16 v[28:31], v[128:131], v[200:203], v[28:31]
	v_mfma_f32_16x16x32_bf16 v[28:31], v[132:135], v[204:207], v[28:31]
	v_mfma_f32_16x16x32_bf16 v[24:27], v[140:143], v[204:207], v[24:27]
	v_mfma_f32_16x16x32_bf16 v[24:27], v[136:139], v[200:203], v[24:27]
	v_mfma_f32_16x16x32_bf16 v[20:23], v[144:147], v[200:203], v[20:23]
	v_mfma_f32_16x16x32_bf16 v[20:23], v[148:151], v[204:207], v[20:23]
	v_mfma_f32_16x16x32_bf16 v[16:19], v[174:177], v[204:207], v[16:19]
	v_mfma_f32_16x16x32_bf16 v[16:19], v[170:173], v[200:203], v[16:19]
	v_mfma_f32_16x16x32_bf16 v[0:3], v[170:173], v[208:211], v[0:3]
	v_mfma_f32_16x16x32_bf16 v[0:3], v[174:177], v[212:215], v[0:3]
	v_mfma_f32_16x16x32_bf16 v[4:7], v[148:151], v[212:215], v[4:7]
	v_mfma_f32_16x16x32_bf16 v[4:7], v[144:147], v[208:211], v[4:7]
	v_mfma_f32_16x16x32_bf16 v[8:11], v[136:139], v[208:211], v[8:11]
	v_mfma_f32_16x16x32_bf16 v[8:11], v[140:143], v[212:215], v[8:11]
	s_barrier
	s_setprio 3
	v_mfma_f32_16x16x32_bf16 v[12:15], v[132:135], v[212:215], v[12:15]
	v_mfma_f32_16x16x32_bf16 v[12:15], v[128:131], v[208:211], v[12:15]
	s_setprio 0
	s_add_i32 s35, s35, 2
	s_add_u32 s24, s24, 0x100
	s_addc_u32 s25, s25, 0
	s_add_u32 s31, s31, 0x100
	s_addc_u32 s34, s34, 0
	s_cmp_gt_u32 s35, 13
	s_cbranch_scc0 .LBB0_1435

.LBB0_1543:
	ds_read_b128 v[128:131], v167
	ds_read_b128 v[154:157], v167 offset:1024
	ds_read_b128 v[172:175], v167 offset:2048
	ds_read_b128 v[176:179], v167 offset:3072
	ds_read_b128 v[180:183], v168
	ds_read_b128 v[184:187], v168 offset:1024
	ds_read_b128 v[188:191], v168 offset:2048
	ds_read_b128 v[192:195], v168 offset:3072
	s_add_u32 s22, s20, 0x1000
	s_addc_u32 s23, s21, 0
	s_cmp_eq_u32 s54, 60
	s_cselect_b32 s27, s13, s23
	s_cselect_b32 s26, s50, s22
	s_cselect_b32 s25, s11, s53
	s_cselect_b32 s24, s51, s52
	v_lshl_add_u64 v[160:161], s[20:21], 0, v[144:145]
	s_add_i32 m0, s19, 0xc000
	s_nop 0
	global_load_lds_dwordx4 v[160:161], off
	v_lshl_add_u64 v[160:161], s[20:21], 0, v[146:147]
	s_add_i32 m0, s19, 0xe000
	s_nop 0
	global_load_lds_dwordx4 v[160:161], off
	ds_read_b128 v[196:199], v169
	ds_read_b128 v[200:203], v169 offset:1024
	ds_read_b128 v[204:207], v169 offset:2048
	ds_read_b128 v[208:211], v169 offset:3072
	ds_read_b128 v[212:215], v169 offset:4096
	ds_read_b128 v[216:219], v169 offset:5120
	ds_read_b128 v[220:223], v169 offset:6144
	ds_read_b128 v[224:227], v169 offset:7168
	s_waitcnt vmcnt(8)
	s_waitcnt lgkmcnt(0)
	s_barrier
	v_mfma_f32_16x16x32_bf16 v[124:127], v[128:131], v[196:199], v[124:127]
	v_mfma_f32_16x16x32_bf16 v[124:127], v[154:157], v[200:203], v[124:127]
	v_mfma_f32_16x16x32_bf16 v[120:123], v[176:179], v[200:203], v[120:123]
	v_mfma_f32_16x16x32_bf16 v[120:123], v[172:175], v[196:199], v[120:123]
	v_mfma_f32_16x16x32_bf16 v[116:119], v[180:183], v[196:199], v[116:119]
	v_mfma_f32_16x16x32_bf16 v[116:119], v[184:187], v[200:203], v[116:119]
	v_mfma_f32_16x16x32_bf16 v[112:115], v[192:195], v[200:203], v[112:115]
	v_mfma_f32_16x16x32_bf16 v[112:115], v[188:191], v[196:199], v[112:115]
	v_mfma_f32_16x16x32_bf16 v[96:99], v[188:191], v[204:207], v[96:99]
	v_mfma_f32_16x16x32_bf16 v[96:99], v[192:195], v[208:211], v[96:99]
	v_mfma_f32_16x16x32_bf16 v[100:103], v[184:187], v[208:211], v[100:103]
	v_mfma_f32_16x16x32_bf16 v[100:103], v[180:183], v[204:207], v[100:103]
	v_mfma_f32_16x16x32_bf16 v[104:107], v[172:175], v[204:207], v[104:107]
	v_mfma_f32_16x16x32_bf16 v[104:107], v[176:179], v[208:211], v[104:107]
	v_mfma_f32_16x16x32_bf16 v[108:111], v[154:157], v[208:211], v[108:111]
	v_mfma_f32_16x16x32_bf16 v[108:111], v[128:131], v[204:207], v[108:111]
	v_mfma_f32_16x16x32_bf16 v[92:95], v[128:131], v[212:215], v[92:95]
	v_mfma_f32_16x16x32_bf16 v[92:95], v[154:157], v[216:219], v[92:95]
	v_mfma_f32_16x16x32_bf16 v[88:91], v[176:179], v[216:219], v[88:91]
	v_mfma_f32_16x16x32_bf16 v[88:91], v[172:175], v[212:215], v[88:91]
	v_mfma_f32_16x16x32_bf16 v[84:87], v[180:183], v[212:215], v[84:87]
	v_mfma_f32_16x16x32_bf16 v[84:87], v[184:187], v[216:219], v[84:87]
	v_mfma_f32_16x16x32_bf16 v[80:83], v[192:195], v[216:219], v[80:83]
	v_mfma_f32_16x16x32_bf16 v[80:83], v[188:191], v[212:215], v[80:83]
	v_mfma_f32_16x16x32_bf16 v[64:67], v[188:191], v[220:223], v[64:67]
	v_mfma_f32_16x16x32_bf16 v[64:67], v[192:195], v[224:227], v[64:67]
	v_mfma_f32_16x16x32_bf16 v[68:71], v[184:187], v[224:227], v[68:71]
	v_mfma_f32_16x16x32_bf16 v[68:71], v[180:183], v[220:223], v[68:71]
	v_mfma_f32_16x16x32_bf16 v[72:75], v[172:175], v[220:223], v[72:75]
	v_mfma_f32_16x16x32_bf16 v[72:75], v[176:179], v[224:227], v[72:75]
	s_barrier
	s_setprio 3
	v_mfma_f32_16x16x32_bf16 v[76:79], v[154:157], v[224:227], v[76:79]
	v_mfma_f32_16x16x32_bf16 v[76:79], v[128:131], v[220:223], v[76:79]
	s_setprio 0
	s_add_i32 s20, s45, s30
	v_lshl_add_u64 v[160:161], s[24:25], 0, v[134:135]
	s_mov_b32 m0, s20
	v_lshl_add_u64 v[164:165], s[24:25], 0, v[138:139]
	global_load_lds_dwordx4 v[160:161], off
	s_add_i32 m0, s20, 0x2000
	s_add_u32 s20, s24, 0x100000
	s_addc_u32 s21, s25, 0
	s_add_i32 s55, s46, s30
	global_load_lds_dwordx4 v[164:165], off
	v_lshl_add_u64 v[196:197], s[20:21], 0, v[134:135]
	s_mov_b32 m0, s55
	v_lshl_add_u64 v[228:229], s[26:27], 0, v[132:133]
	global_load_lds_dwordx4 v[196:197], off
	v_lshl_add_u64 v[196:197], s[20:21], 0, v[138:139]
	s_add_i32 m0, s55, 0x2000
	v_lshl_add_u64 v[230:231], s[26:27], 0, v[136:137]
	global_load_lds_dwordx4 v[196:197], off
	s_mov_b32 m0, s19
	s_nop 0
	global_load_lds_dwordx4 v[228:229], off
	s_mov_b32 m0, s36
	s_nop 0
	global_load_lds_dwordx4 v[230:231], off
	ds_read_b128 v[196:199], v169 offset:16384
	ds_read_b128 v[200:203], v169 offset:17408
	ds_read_b128 v[204:207], v169 offset:18432
	ds_read_b128 v[208:211], v169 offset:19456
	ds_read_b128 v[212:215], v169 offset:20480
	ds_read_b128 v[216:219], v169 offset:21504
	ds_read_b128 v[220:223], v169 offset:22528
	ds_read_b128 v[224:227], v169 offset:23552
	s_waitcnt vmcnt(8)
	s_waitcnt lgkmcnt(0)
	s_barrier
	v_mfma_f32_16x16x32_bf16 v[60:63], v[128:131], v[196:199], v[60:63]
	v_mfma_f32_16x16x32_bf16 v[60:63], v[154:157], v[200:203], v[60:63]
	v_mfma_f32_16x16x32_bf16 v[56:59], v[176:179], v[200:203], v[56:59]
	v_mfma_f32_16x16x32_bf16 v[56:59], v[172:175], v[196:199], v[56:59]
	v_mfma_f32_16x16x32_bf16 v[52:55], v[180:183], v[196:199], v[52:55]
	v_mfma_f32_16x16x32_bf16 v[52:55], v[184:187], v[200:203], v[52:55]
	v_mfma_f32_16x16x32_bf16 v[48:51], v[192:195], v[200:203], v[48:51]
	v_mfma_f32_16x16x32_bf16 v[48:51], v[188:191], v[196:199], v[48:51]
	v_mfma_f32_16x16x32_bf16 v[32:35], v[188:191], v[204:207], v[32:35]
	v_mfma_f32_16x16x32_bf16 v[32:35], v[192:195], v[208:211], v[32:35]
	v_mfma_f32_16x16x32_bf16 v[36:39], v[184:187], v[208:211], v[36:39]
	v_mfma_f32_16x16x32_bf16 v[36:39], v[180:183], v[204:207], v[36:39]
	v_mfma_f32_16x16x32_bf16 v[40:43], v[172:175], v[204:207], v[40:43]
	v_mfma_f32_16x16x32_bf16 v[40:43], v[176:179], v[208:211], v[40:43]
	v_mfma_f32_16x16x32_bf16 v[44:47], v[154:157], v[208:211], v[44:47]
	v_mfma_f32_16x16x32_bf16 v[44:47], v[128:131], v[204:207], v[44:47]
	v_mfma_f32_16x16x32_bf16 v[28:31], v[128:131], v[212:215], v[28:31]
	v_mfma_f32_16x16x32_bf16 v[28:31], v[154:157], v[216:219], v[28:31]
	v_mfma_f32_16x16x32_bf16 v[24:27], v[176:179], v[216:219], v[24:27]
	v_mfma_f32_16x16x32_bf16 v[24:27], v[172:175], v[212:215], v[24:27]
	v_mfma_f32_16x16x32_bf16 v[20:23], v[180:183], v[212:215], v[20:23]
	v_mfma_f32_16x16x32_bf16 v[20:23], v[184:187], v[216:219], v[20:23]
	v_mfma_f32_16x16x32_bf16 v[16:19], v[192:195], v[216:219], v[16:19]
	v_mfma_f32_16x16x32_bf16 v[16:19], v[188:191], v[212:215], v[16:19]
	v_mfma_f32_16x16x32_bf16 v[0:3], v[188:191], v[220:223], v[0:3]
	v_mfma_f32_16x16x32_bf16 v[0:3], v[192:195], v[224:227], v[0:3]
	v_mfma_f32_16x16x32_bf16 v[4:7], v[184:187], v[224:227], v[4:7]
	v_mfma_f32_16x16x32_bf16 v[4:7], v[180:183], v[220:223], v[4:7]
	v_mfma_f32_16x16x32_bf16 v[8:11], v[172:175], v[220:223], v[8:11]
	v_mfma_f32_16x16x32_bf16 v[8:11], v[176:179], v[224:227], v[8:11]
	s_barrier
	s_setprio 3
	v_mfma_f32_16x16x32_bf16 v[12:15], v[154:157], v[224:227], v[12:15]
	v_mfma_f32_16x16x32_bf16 v[12:15], v[128:131], v[220:223], v[12:15]
	s_setprio 0
	s_add_i32 s55, 0, 0x18000
	v_add_u32_e32 v153, s55, v159
	s_add_i32 s56, 0, 0x1c000
	ds_read_b128 v[128:131], v153
	ds_read_b128 v[154:157], v153 offset:1024
	ds_read_b128 v[172:175], v153 offset:2048
	ds_read_b128 v[176:179], v153 offset:3072
	v_add_u32_e32 v153, s56, v159
	ds_read_b128 v[180:183], v153
	ds_read_b128 v[184:187], v153 offset:1024
	ds_read_b128 v[188:191], v153 offset:2048
	ds_read_b128 v[192:195], v153 offset:3072
	s_add_u32 s20, s26, 0x100000
	s_addc_u32 s21, s27, 0
	s_mov_b32 m0, s37
	v_lshl_add_u64 v[196:197], s[20:21], 0, v[132:133]
	global_load_lds_dwordx4 v[196:197], off
	v_lshl_add_u64 v[196:197], s[20:21], 0, v[136:137]
	s_mov_b32 m0, s38
	s_nop 0
	global_load_lds_dwordx4 v[196:197], off
	ds_read_b128 v[196:199], v169 offset:32768
	ds_read_b128 v[200:203], v169 offset:33792
	ds_read_b128 v[204:207], v169 offset:34816
	ds_read_b128 v[208:211], v169 offset:35840
	ds_read_b128 v[212:215], v169 offset:36864
	ds_read_b128 v[216:219], v169 offset:37888
	ds_read_b128 v[220:223], v169 offset:38912
	ds_read_b128 v[224:227], v169 offset:39936
	s_waitcnt vmcnt(8)
	s_waitcnt lgkmcnt(0)
	s_barrier
	v_mfma_f32_16x16x32_bf16 v[124:127], v[128:131], v[196:199], v[124:127]
	v_mfma_f32_16x16x32_bf16 v[124:127], v[154:157], v[200:203], v[124:127]
	v_mfma_f32_16x16x32_bf16 v[120:123], v[176:179], v[200:203], v[120:123]
	v_mfma_f32_16x16x32_bf16 v[120:123], v[172:175], v[196:199], v[120:123]
	v_mfma_f32_16x16x32_bf16 v[116:119], v[180:183], v[196:199], v[116:119]
	v_mfma_f32_16x16x32_bf16 v[116:119], v[184:187], v[200:203], v[116:119]
	v_mfma_f32_16x16x32_bf16 v[112:115], v[192:195], v[200:203], v[112:115]
	v_mfma_f32_16x16x32_bf16 v[112:115], v[188:191], v[196:199], v[112:115]
	v_mfma_f32_16x16x32_bf16 v[96:99], v[188:191], v[204:207], v[96:99]
	v_mfma_f32_16x16x32_bf16 v[96:99], v[192:195], v[208:211], v[96:99]
	v_mfma_f32_16x16x32_bf16 v[100:103], v[184:187], v[208:211], v[100:103]
	v_mfma_f32_16x16x32_bf16 v[100:103], v[180:183], v[204:207], v[100:103]
	v_mfma_f32_16x16x32_bf16 v[104:107], v[172:175], v[204:207], v[104:107]
	v_mfma_f32_16x16x32_bf16 v[104:107], v[176:179], v[208:211], v[104:107]
	v_mfma_f32_16x16x32_bf16 v[108:111], v[154:157], v[208:211], v[108:111]
	v_mfma_f32_16x16x32_bf16 v[108:111], v[128:131], v[204:207], v[108:111]
	v_mfma_f32_16x16x32_bf16 v[92:95], v[128:131], v[212:215], v[92:95]
	v_mfma_f32_16x16x32_bf16 v[92:95], v[154:157], v[216:219], v[92:95]
	v_mfma_f32_16x16x32_bf16 v[88:91], v[176:179], v[216:219], v[88:91]
	v_mfma_f32_16x16x32_bf16 v[88:91], v[172:175], v[212:215], v[88:91]
	v_mfma_f32_16x16x32_bf16 v[84:87], v[180:183], v[212:215], v[84:87]
	v_mfma_f32_16x16x32_bf16 v[84:87], v[184:187], v[216:219], v[84:87]
	v_mfma_f32_16x16x32_bf16 v[80:83], v[192:195], v[216:219], v[80:83]
	v_mfma_f32_16x16x32_bf16 v[80:83], v[188:191], v[212:215], v[80:83]
	v_mfma_f32_16x16x32_bf16 v[64:67], v[188:191], v[220:223], v[64:67]
	v_mfma_f32_16x16x32_bf16 v[64:67], v[192:195], v[224:227], v[64:67]
	v_mfma_f32_16x16x32_bf16 v[68:71], v[184:187], v[224:227], v[68:71]
	v_mfma_f32_16x16x32_bf16 v[68:71], v[180:183], v[220:223], v[68:71]
	v_mfma_f32_16x16x32_bf16 v[72:75], v[172:175], v[220:223], v[72:75]
	v_mfma_f32_16x16x32_bf16 v[72:75], v[176:179], v[224:227], v[72:75]
	s_barrier
	s_setprio 3
	v_mfma_f32_16x16x32_bf16 v[76:79], v[154:157], v[224:227], v[76:79]
	v_mfma_f32_16x16x32_bf16 v[76:79], v[128:131], v[220:223], v[76:79]
	s_setprio 0
	s_add_i32 s20, s55, s30
	v_lshl_add_u64 v[160:161], v[160:161], 0, s[8:9]
	s_mov_b32 m0, s20
	s_nop 0
	global_load_lds_dwordx4 v[160:161], off
	s_add_i32 m0, s20, 0x2000
	s_add_u32 s20, s24, 0x100800
	v_lshl_add_u64 v[160:161], v[164:165], 0, s[8:9]
	s_addc_u32 s21, s25, 0
	s_add_i32 s24, s56, s30
	global_load_lds_dwordx4 v[160:161], off
	v_lshl_add_u64 v[160:161], s[20:21], 0, v[134:135]
	s_mov_b32 m0, s24
	s_nop 0
	global_load_lds_dwordx4 v[160:161], off
	v_lshl_add_u64 v[160:161], s[20:21], 0, v[138:139]
	s_add_i32 m0, s24, 0x2000
	s_nop 0
	global_load_lds_dwordx4 v[160:161], off
	v_lshl_add_u64 v[160:161], v[228:229], 0, s[8:9]
	s_mov_b32 m0, s41
	s_nop 0
	global_load_lds_dwordx4 v[160:161], off
	v_lshl_add_u64 v[160:161], v[230:231], 0, s[8:9]
	s_mov_b32 m0, s42
	s_nop 0
	global_load_lds_dwordx4 v[160:161], off
	ds_read_b128 v[196:199], v169 offset:49152
	ds_read_b128 v[200:203], v169 offset:50176
	ds_read_b128 v[204:207], v169 offset:51200
	ds_read_b128 v[208:211], v169 offset:52224
	ds_read_b128 v[212:215], v169 offset:53248
	ds_read_b128 v[216:219], v169 offset:54272
	ds_read_b128 v[220:223], v169 offset:55296
	ds_read_b128 v[224:227], v169 offset:56320
	s_waitcnt vmcnt(8)
	s_waitcnt lgkmcnt(0)
	s_barrier
	v_mfma_f32_16x16x32_bf16 v[60:63], v[128:131], v[196:199], v[60:63]
	v_mfma_f32_16x16x32_bf16 v[60:63], v[154:157], v[200:203], v[60:63]
	v_mfma_f32_16x16x32_bf16 v[56:59], v[176:179], v[200:203], v[56:59]
	v_mfma_f32_16x16x32_bf16 v[56:59], v[172:175], v[196:199], v[56:59]
	v_mfma_f32_16x16x32_bf16 v[52:55], v[180:183], v[196:199], v[52:55]
	v_mfma_f32_16x16x32_bf16 v[52:55], v[184:187], v[200:203], v[52:55]
	v_mfma_f32_16x16x32_bf16 v[48:51], v[192:195], v[200:203], v[48:51]
	v_mfma_f32_16x16x32_bf16 v[48:51], v[188:191], v[196:199], v[48:51]
	v_mfma_f32_16x16x32_bf16 v[32:35], v[188:191], v[204:207], v[32:35]
	v_mfma_f32_16x16x32_bf16 v[32:35], v[192:195], v[208:211], v[32:35]
	v_mfma_f32_16x16x32_bf16 v[36:39], v[184:187], v[208:211], v[36:39]
	v_mfma_f32_16x16x32_bf16 v[36:39], v[180:183], v[204:207], v[36:39]
	v_mfma_f32_16x16x32_bf16 v[40:43], v[172:175], v[204:207], v[40:43]
	v_mfma_f32_16x16x32_bf16 v[40:43], v[176:179], v[208:211], v[40:43]
	v_mfma_f32_16x16x32_bf16 v[44:47], v[154:157], v[208:211], v[44:47]
	v_mfma_f32_16x16x32_bf16 v[44:47], v[128:131], v[204:207], v[44:47]
	v_mfma_f32_16x16x32_bf16 v[28:31], v[128:131], v[212:215], v[28:31]
	v_mfma_f32_16x16x32_bf16 v[28:31], v[154:157], v[216:219], v[28:31]
	v_mfma_f32_16x16x32_bf16 v[24:27], v[176:179], v[216:219], v[24:27]
	v_mfma_f32_16x16x32_bf16 v[24:27], v[172:175], v[212:215], v[24:27]
	v_mfma_f32_16x16x32_bf16 v[20:23], v[180:183], v[212:215], v[20:23]
	v_mfma_f32_16x16x32_bf16 v[20:23], v[184:187], v[216:219], v[20:23]
	v_mfma_f32_16x16x32_bf16 v[16:19], v[192:195], v[216:219], v[16:19]
	v_mfma_f32_16x16x32_bf16 v[16:19], v[188:191], v[212:215], v[16:19]
	v_mfma_f32_16x16x32_bf16 v[0:3], v[188:191], v[220:223], v[0:3]
	v_mfma_f32_16x16x32_bf16 v[0:3], v[192:195], v[224:227], v[0:3]
	v_mfma_f32_16x16x32_bf16 v[4:7], v[184:187], v[224:227], v[4:7]
	v_mfma_f32_16x16x32_bf16 v[4:7], v[180:183], v[220:223], v[4:7]
	v_mfma_f32_16x16x32_bf16 v[8:11], v[172:175], v[220:223], v[8:11]
	v_mfma_f32_16x16x32_bf16 v[8:11], v[176:179], v[224:227], v[8:11]
	s_barrier
	s_setprio 3
	v_mfma_f32_16x16x32_bf16 v[12:15], v[154:157], v[224:227], v[12:15]
	v_mfma_f32_16x16x32_bf16 v[12:15], v[128:131], v[220:223], v[12:15]
	s_setprio 0
	s_add_i32 s54, s54, 2
	s_add_u32 s52, s52, 0x1000
	s_addc_u32 s53, s53, 0
	s_cmp_gt_u32 s54, 61
	s_mov_b64 s[20:21], s[22:23]
	s_cbranch_scc0 .LBB0_1543

.LBB0_1625:
	ds_read_b128 v[128:131], v177
	ds_read_b128 v[132:135], v177 offset:1024
	ds_read_b128 v[136:139], v177 offset:2048
	ds_read_b128 v[140:143], v177 offset:3072
	ds_read_b128 v[144:147], v178
	ds_read_b128 v[148:151], v178 offset:1024
	ds_read_b128 v[170:173], v178 offset:2048
	ds_read_b128 v[182:185], v178 offset:3072
	s_add_u32 s24, s22, 0xffc00800
	s_addc_u32 s25, s23, -1
	s_cmpk_eq_i32 s57, 0xfc
	s_cselect_b32 s27, s29, s25
	s_cselect_b32 s26, s53, s24
	s_cselect_b32 s25, s17, s56
	s_cselect_b32 s24, s54, s55
	v_lshl_add_u64 v[186:187], s[22:23], 0, v[162:163]
	s_add_i32 m0, s38, 0xc000
	s_nop 0
	global_load_lds_dwordx4 v[186:187], off
	v_lshl_add_u64 v[186:187], s[22:23], 0, v[164:165]
	s_add_i32 m0, s38, 0xe000
	s_nop 0
	global_load_lds_dwordx4 v[186:187], off
	ds_read_b128 v[186:189], v179
	ds_read_b128 v[190:193], v179 offset:1024
	ds_read_b128 v[194:197], v179 offset:2048
	ds_read_b128 v[198:201], v179 offset:3072
	ds_read_b128 v[202:205], v179 offset:4096
	ds_read_b128 v[206:209], v179 offset:5120
	ds_read_b128 v[210:213], v179 offset:6144
	ds_read_b128 v[214:217], v179 offset:7168
	s_waitcnt vmcnt(8)
	s_waitcnt lgkmcnt(0)
	s_barrier
	v_mfma_f32_16x16x32_bf16 v[124:127], v[128:131], v[186:189], v[124:127]
	v_mfma_f32_16x16x32_bf16 v[124:127], v[132:135], v[190:193], v[124:127]
	v_mfma_f32_16x16x32_bf16 v[120:123], v[140:143], v[190:193], v[120:123]
	v_mfma_f32_16x16x32_bf16 v[120:123], v[136:139], v[186:189], v[120:123]
	v_mfma_f32_16x16x32_bf16 v[116:119], v[144:147], v[186:189], v[116:119]
	v_mfma_f32_16x16x32_bf16 v[116:119], v[148:151], v[190:193], v[116:119]
	v_mfma_f32_16x16x32_bf16 v[112:115], v[182:185], v[190:193], v[112:115]
	v_mfma_f32_16x16x32_bf16 v[112:115], v[170:173], v[186:189], v[112:115]
	v_mfma_f32_16x16x32_bf16 v[96:99], v[170:173], v[194:197], v[96:99]
	v_mfma_f32_16x16x32_bf16 v[96:99], v[182:185], v[198:201], v[96:99]
	v_mfma_f32_16x16x32_bf16 v[100:103], v[148:151], v[198:201], v[100:103]
	v_mfma_f32_16x16x32_bf16 v[100:103], v[144:147], v[194:197], v[100:103]
	v_mfma_f32_16x16x32_bf16 v[104:107], v[136:139], v[194:197], v[104:107]
	v_mfma_f32_16x16x32_bf16 v[104:107], v[140:143], v[198:201], v[104:107]
	v_mfma_f32_16x16x32_bf16 v[108:111], v[132:135], v[198:201], v[108:111]
	v_mfma_f32_16x16x32_bf16 v[108:111], v[128:131], v[194:197], v[108:111]
	v_mfma_f32_16x16x32_bf16 v[92:95], v[128:131], v[202:205], v[92:95]
	v_mfma_f32_16x16x32_bf16 v[92:95], v[132:135], v[206:209], v[92:95]
	v_mfma_f32_16x16x32_bf16 v[88:91], v[140:143], v[206:209], v[88:91]
	v_mfma_f32_16x16x32_bf16 v[88:91], v[136:139], v[202:205], v[88:91]
	v_mfma_f32_16x16x32_bf16 v[84:87], v[144:147], v[202:205], v[84:87]
	v_mfma_f32_16x16x32_bf16 v[84:87], v[148:151], v[206:209], v[84:87]
	v_mfma_f32_16x16x32_bf16 v[80:83], v[182:185], v[206:209], v[80:83]
	v_mfma_f32_16x16x32_bf16 v[80:83], v[170:173], v[202:205], v[80:83]
	v_mfma_f32_16x16x32_bf16 v[64:67], v[170:173], v[210:213], v[64:67]
	v_mfma_f32_16x16x32_bf16 v[64:67], v[182:185], v[214:217], v[64:67]
	v_mfma_f32_16x16x32_bf16 v[68:71], v[148:151], v[214:217], v[68:71]
	v_mfma_f32_16x16x32_bf16 v[68:71], v[144:147], v[210:213], v[68:71]
	v_mfma_f32_16x16x32_bf16 v[72:75], v[136:139], v[210:213], v[72:75]
	v_mfma_f32_16x16x32_bf16 v[72:75], v[140:143], v[214:217], v[72:75]
	s_barrier
	s_setprio 3
	v_mfma_f32_16x16x32_bf16 v[76:79], v[132:135], v[214:217], v[76:79]
	v_mfma_f32_16x16x32_bf16 v[76:79], v[128:131], v[210:213], v[76:79]
	s_setprio 0
	s_add_i32 s58, s48, s37
	v_lshl_add_u64 v[218:219], s[24:25], 0, v[154:155]
	s_mov_b32 m0, s58
	v_lshl_add_u64 v[220:221], s[24:25], 0, v[158:159]
	global_load_lds_dwordx4 v[218:219], off
	s_add_i32 m0, s58, 0x2000
	s_add_u32 s58, s24, 0x400000
	s_addc_u32 s59, s25, 0
	s_add_i32 s60, s49, s37
	global_load_lds_dwordx4 v[220:221], off
	v_lshl_add_u64 v[186:187], s[58:59], 0, v[154:155]
	s_mov_b32 m0, s60
	v_lshl_add_u64 v[222:223], s[26:27], 0, v[152:153]
	global_load_lds_dwordx4 v[186:187], off
	v_lshl_add_u64 v[186:187], s[58:59], 0, v[158:159]
	s_add_i32 m0, s60, 0x2000
	v_lshl_add_u64 v[224:225], s[26:27], 0, v[156:157]
	global_load_lds_dwordx4 v[186:187], off
	s_mov_b32 m0, s38
	s_nop 0
	global_load_lds_dwordx4 v[222:223], off
	s_mov_b32 m0, s39
	s_nop 0
	global_load_lds_dwordx4 v[224:225], off
	ds_read_b128 v[186:189], v179 offset:16384
	ds_read_b128 v[190:193], v179 offset:17408
	ds_read_b128 v[194:197], v179 offset:18432
	ds_read_b128 v[198:201], v179 offset:19456
	ds_read_b128 v[202:205], v179 offset:20480
	ds_read_b128 v[206:209], v179 offset:21504
	ds_read_b128 v[210:213], v179 offset:22528
	ds_read_b128 v[214:217], v179 offset:23552
	s_waitcnt vmcnt(8)
	s_waitcnt lgkmcnt(0)
	s_barrier
	v_mfma_f32_16x16x32_bf16 v[60:63], v[128:131], v[186:189], v[60:63]
	v_mfma_f32_16x16x32_bf16 v[60:63], v[132:135], v[190:193], v[60:63]
	v_mfma_f32_16x16x32_bf16 v[56:59], v[140:143], v[190:193], v[56:59]
	v_mfma_f32_16x16x32_bf16 v[56:59], v[136:139], v[186:189], v[56:59]
	v_mfma_f32_16x16x32_bf16 v[52:55], v[144:147], v[186:189], v[52:55]
	v_mfma_f32_16x16x32_bf16 v[52:55], v[148:151], v[190:193], v[52:55]
	v_mfma_f32_16x16x32_bf16 v[48:51], v[182:185], v[190:193], v[48:51]
	v_mfma_f32_16x16x32_bf16 v[48:51], v[170:173], v[186:189], v[48:51]
	v_mfma_f32_16x16x32_bf16 v[32:35], v[170:173], v[194:197], v[32:35]
	v_mfma_f32_16x16x32_bf16 v[32:35], v[182:185], v[198:201], v[32:35]
	v_mfma_f32_16x16x32_bf16 v[36:39], v[148:151], v[198:201], v[36:39]
	v_mfma_f32_16x16x32_bf16 v[36:39], v[144:147], v[194:197], v[36:39]
	v_mfma_f32_16x16x32_bf16 v[40:43], v[136:139], v[194:197], v[40:43]
	v_mfma_f32_16x16x32_bf16 v[40:43], v[140:143], v[198:201], v[40:43]
	v_mfma_f32_16x16x32_bf16 v[44:47], v[132:135], v[198:201], v[44:47]
	v_mfma_f32_16x16x32_bf16 v[44:47], v[128:131], v[194:197], v[44:47]
	v_mfma_f32_16x16x32_bf16 v[28:31], v[128:131], v[202:205], v[28:31]
	v_mfma_f32_16x16x32_bf16 v[28:31], v[132:135], v[206:209], v[28:31]
	v_mfma_f32_16x16x32_bf16 v[24:27], v[140:143], v[206:209], v[24:27]
	v_mfma_f32_16x16x32_bf16 v[24:27], v[136:139], v[202:205], v[24:27]
	v_mfma_f32_16x16x32_bf16 v[20:23], v[144:147], v[202:205], v[20:23]
	v_mfma_f32_16x16x32_bf16 v[20:23], v[148:151], v[206:209], v[20:23]
	v_mfma_f32_16x16x32_bf16 v[16:19], v[182:185], v[206:209], v[16:19]
	v_mfma_f32_16x16x32_bf16 v[16:19], v[170:173], v[202:205], v[16:19]
	v_mfma_f32_16x16x32_bf16 v[0:3], v[170:173], v[210:213], v[0:3]
	v_mfma_f32_16x16x32_bf16 v[0:3], v[182:185], v[214:217], v[0:3]
	v_mfma_f32_16x16x32_bf16 v[4:7], v[148:151], v[214:217], v[4:7]
	v_mfma_f32_16x16x32_bf16 v[4:7], v[144:147], v[210:213], v[4:7]
	v_mfma_f32_16x16x32_bf16 v[8:11], v[136:139], v[210:213], v[8:11]
	v_mfma_f32_16x16x32_bf16 v[8:11], v[140:143], v[214:217], v[8:11]
	s_barrier
	s_setprio 3
	v_mfma_f32_16x16x32_bf16 v[12:15], v[132:135], v[214:217], v[12:15]
	v_mfma_f32_16x16x32_bf16 v[12:15], v[128:131], v[210:213], v[12:15]
	s_setprio 0
	s_add_i32 s58, 0, 0x18000
	s_add_i32 s59, 0, 0x1c000
	v_add_u32_e32 v140, s58, v174
	v_add_u32_e32 v181, s59, v174
	ds_read_b128 v[128:131], v140
	ds_read_b128 v[132:135], v140 offset:1024
	ds_read_b128 v[136:139], v140 offset:2048
	ds_read_b128 v[140:143], v140 offset:3072
	ds_read_b128 v[144:147], v181
	ds_read_b128 v[148:151], v181 offset:1024
	ds_read_b128 v[170:173], v181 offset:2048
	ds_read_b128 v[182:185], v181 offset:3072
	s_add_u32 s26, s26, 0x400000
	s_addc_u32 s27, s27, 0
	s_mov_b32 m0, s40
	v_lshl_add_u64 v[186:187], s[26:27], 0, v[152:153]
	global_load_lds_dwordx4 v[186:187], off
	v_lshl_add_u64 v[186:187], s[26:27], 0, v[156:157]
	s_mov_b32 m0, s41
	s_nop 0
	global_load_lds_dwordx4 v[186:187], off
	ds_read_b128 v[186:189], v179 offset:32768
	ds_read_b128 v[190:193], v179 offset:33792
	ds_read_b128 v[194:197], v179 offset:34816
	ds_read_b128 v[198:201], v179 offset:35840
	ds_read_b128 v[202:205], v179 offset:36864
	ds_read_b128 v[206:209], v179 offset:37888
	ds_read_b128 v[210:213], v179 offset:38912
	ds_read_b128 v[214:217], v179 offset:39936
	s_waitcnt vmcnt(8)
	s_waitcnt lgkmcnt(0)
	s_barrier
	v_mfma_f32_16x16x32_bf16 v[124:127], v[128:131], v[186:189], v[124:127]
	v_mfma_f32_16x16x32_bf16 v[124:127], v[132:135], v[190:193], v[124:127]
	v_mfma_f32_16x16x32_bf16 v[120:123], v[140:143], v[190:193], v[120:123]
	v_mfma_f32_16x16x32_bf16 v[120:123], v[136:139], v[186:189], v[120:123]
	v_mfma_f32_16x16x32_bf16 v[116:119], v[144:147], v[186:189], v[116:119]
	v_mfma_f32_16x16x32_bf16 v[116:119], v[148:151], v[190:193], v[116:119]
	v_mfma_f32_16x16x32_bf16 v[112:115], v[182:185], v[190:193], v[112:115]
	v_mfma_f32_16x16x32_bf16 v[112:115], v[170:173], v[186:189], v[112:115]
	v_mfma_f32_16x16x32_bf16 v[96:99], v[170:173], v[194:197], v[96:99]
	v_mfma_f32_16x16x32_bf16 v[96:99], v[182:185], v[198:201], v[96:99]
	v_mfma_f32_16x16x32_bf16 v[100:103], v[148:151], v[198:201], v[100:103]
	v_mfma_f32_16x16x32_bf16 v[100:103], v[144:147], v[194:197], v[100:103]
	v_mfma_f32_16x16x32_bf16 v[104:107], v[136:139], v[194:197], v[104:107]
	v_mfma_f32_16x16x32_bf16 v[104:107], v[140:143], v[198:201], v[104:107]
	v_mfma_f32_16x16x32_bf16 v[108:111], v[132:135], v[198:201], v[108:111]
	v_mfma_f32_16x16x32_bf16 v[108:111], v[128:131], v[194:197], v[108:111]
	v_mfma_f32_16x16x32_bf16 v[92:95], v[128:131], v[202:205], v[92:95]
	v_mfma_f32_16x16x32_bf16 v[92:95], v[132:135], v[206:209], v[92:95]
	v_mfma_f32_16x16x32_bf16 v[88:91], v[140:143], v[206:209], v[88:91]
	v_mfma_f32_16x16x32_bf16 v[88:91], v[136:139], v[202:205], v[88:91]
	v_mfma_f32_16x16x32_bf16 v[84:87], v[144:147], v[202:205], v[84:87]
	v_mfma_f32_16x16x32_bf16 v[84:87], v[148:151], v[206:209], v[84:87]
	v_mfma_f32_16x16x32_bf16 v[80:83], v[182:185], v[206:209], v[80:83]
	v_mfma_f32_16x16x32_bf16 v[80:83], v[170:173], v[202:205], v[80:83]
	v_mfma_f32_16x16x32_bf16 v[64:67], v[170:173], v[210:213], v[64:67]
	v_mfma_f32_16x16x32_bf16 v[64:67], v[182:185], v[214:217], v[64:67]
	v_mfma_f32_16x16x32_bf16 v[68:71], v[148:151], v[214:217], v[68:71]
	v_mfma_f32_16x16x32_bf16 v[68:71], v[144:147], v[210:213], v[68:71]
	v_mfma_f32_16x16x32_bf16 v[72:75], v[136:139], v[210:213], v[72:75]
	v_mfma_f32_16x16x32_bf16 v[72:75], v[140:143], v[214:217], v[72:75]
	s_barrier
	s_setprio 3
	v_mfma_f32_16x16x32_bf16 v[76:79], v[132:135], v[214:217], v[76:79]
	v_mfma_f32_16x16x32_bf16 v[76:79], v[128:131], v[210:213], v[76:79]
	s_setprio 0
	s_add_i32 s26, s58, s37
	v_lshl_add_u64 v[186:187], v[218:219], 0, s[14:15]
	s_mov_b32 m0, s26
	s_nop 0
	global_load_lds_dwordx4 v[186:187], off
	s_add_i32 m0, s26, 0x2000
	s_add_u32 s24, s24, 0x400800
	v_lshl_add_u64 v[186:187], v[220:221], 0, s[14:15]
	s_addc_u32 s25, s25, 0
	s_add_i32 s26, s59, s37
	global_load_lds_dwordx4 v[186:187], off
	v_lshl_add_u64 v[186:187], s[24:25], 0, v[154:155]
	s_mov_b32 m0, s26
	s_nop 0
	global_load_lds_dwordx4 v[186:187], off
	v_lshl_add_u64 v[186:187], s[24:25], 0, v[158:159]
	s_add_i32 m0, s26, 0x2000
	s_nop 0
	global_load_lds_dwordx4 v[186:187], off
	v_lshl_add_u64 v[186:187], v[222:223], 0, s[14:15]
	s_mov_b32 m0, s43
	s_nop 0
	global_load_lds_dwordx4 v[186:187], off
	v_lshl_add_u64 v[186:187], v[224:225], 0, s[14:15]
	s_mov_b32 m0, s44
	s_nop 0
	global_load_lds_dwordx4 v[186:187], off
	ds_read_b128 v[186:189], v179 offset:49152
	ds_read_b128 v[190:193], v179 offset:50176
	ds_read_b128 v[194:197], v179 offset:51200
	ds_read_b128 v[198:201], v179 offset:52224
	ds_read_b128 v[202:205], v179 offset:53248
	ds_read_b128 v[206:209], v179 offset:54272
	ds_read_b128 v[210:213], v179 offset:55296
	ds_read_b128 v[214:217], v179 offset:56320
	s_waitcnt vmcnt(8)
	s_waitcnt lgkmcnt(0)
	s_barrier
	v_mfma_f32_16x16x32_bf16 v[60:63], v[128:131], v[186:189], v[60:63]
	v_mfma_f32_16x16x32_bf16 v[60:63], v[132:135], v[190:193], v[60:63]
	v_mfma_f32_16x16x32_bf16 v[56:59], v[140:143], v[190:193], v[56:59]
	v_mfma_f32_16x16x32_bf16 v[56:59], v[136:139], v[186:189], v[56:59]
	v_mfma_f32_16x16x32_bf16 v[52:55], v[144:147], v[186:189], v[52:55]
	v_mfma_f32_16x16x32_bf16 v[52:55], v[148:151], v[190:193], v[52:55]
	v_mfma_f32_16x16x32_bf16 v[48:51], v[182:185], v[190:193], v[48:51]
	v_mfma_f32_16x16x32_bf16 v[48:51], v[170:173], v[186:189], v[48:51]
	v_mfma_f32_16x16x32_bf16 v[32:35], v[170:173], v[194:197], v[32:35]
	v_mfma_f32_16x16x32_bf16 v[32:35], v[182:185], v[198:201], v[32:35]
	v_mfma_f32_16x16x32_bf16 v[36:39], v[148:151], v[198:201], v[36:39]
	v_mfma_f32_16x16x32_bf16 v[36:39], v[144:147], v[194:197], v[36:39]
	v_mfma_f32_16x16x32_bf16 v[40:43], v[136:139], v[194:197], v[40:43]
	v_mfma_f32_16x16x32_bf16 v[40:43], v[140:143], v[198:201], v[40:43]
	v_mfma_f32_16x16x32_bf16 v[44:47], v[132:135], v[198:201], v[44:47]
	v_mfma_f32_16x16x32_bf16 v[44:47], v[128:131], v[194:197], v[44:47]
	v_mfma_f32_16x16x32_bf16 v[28:31], v[128:131], v[202:205], v[28:31]
	v_mfma_f32_16x16x32_bf16 v[28:31], v[132:135], v[206:209], v[28:31]
	v_mfma_f32_16x16x32_bf16 v[24:27], v[140:143], v[206:209], v[24:27]
	v_mfma_f32_16x16x32_bf16 v[24:27], v[136:139], v[202:205], v[24:27]
	v_mfma_f32_16x16x32_bf16 v[20:23], v[144:147], v[202:205], v[20:23]
	v_mfma_f32_16x16x32_bf16 v[20:23], v[148:151], v[206:209], v[20:23]
	v_mfma_f32_16x16x32_bf16 v[16:19], v[182:185], v[206:209], v[16:19]
	v_mfma_f32_16x16x32_bf16 v[16:19], v[170:173], v[202:205], v[16:19]
	v_mfma_f32_16x16x32_bf16 v[0:3], v[170:173], v[210:213], v[0:3]
	v_mfma_f32_16x16x32_bf16 v[0:3], v[182:185], v[214:217], v[0:3]
	v_mfma_f32_16x16x32_bf16 v[4:7], v[148:151], v[214:217], v[4:7]
	v_mfma_f32_16x16x32_bf16 v[4:7], v[144:147], v[210:213], v[4:7]
	v_mfma_f32_16x16x32_bf16 v[8:11], v[136:139], v[210:213], v[8:11]
	v_mfma_f32_16x16x32_bf16 v[8:11], v[140:143], v[214:217], v[8:11]
	s_barrier
	s_setprio 3
	v_mfma_f32_16x16x32_bf16 v[12:15], v[132:135], v[214:217], v[12:15]
	v_mfma_f32_16x16x32_bf16 v[12:15], v[128:131], v[210:213], v[12:15]
	s_setprio 0
	s_add_i32 s57, s57, 2
	s_add_u32 s22, s22, 0x1000
	s_addc_u32 s23, s23, 0
	s_add_u32 s55, s55, 0x1000
	s_addc_u32 s56, s56, 0
	s_cmpk_gt_u32 s57, 0xfd
	s_cbranch_scc0 .LBB0_1625
